# adds: attention tile loop: dropped the m0 save/restore around each LDS-DMA block (m0 has no other reader), folded the row-sum chain moves
# speedup vs baseline: 1.0406x; 1.0028x over previous
; __device__ __forceinline__ float bf_lo(unsigned u) { return __uint_as_float(u << 16); }
; __device__ __forceinline__ float bf_hi(unsigned u) { return __uint_as_float(u & 0xffff0000u); }
; __device__ __forceinline__ int lane_op() { unsigned z = 0u; asm volatile("" : "+v"(z)); return (int)__builtin_amdgcn_mbcnt_hi(~0u, __builtin_amdgcn_mbcnt_lo(~0u, z)); }
; __device__ __forceinline__ float swap_add(float v) { auto rr = __builtin_amdgcn_permlane32_swap(__float_as_uint(v), __float_as_uint(v), false, false); return __uint_as_float(rr[0]) + __uint_as_float(rr[1]); }
; template <bool STORE> __device__ __forceinline__ void attn_unit(LAS unsigned char* lds, bf16_t* Q, const bf16_t* Kg, const bf16_t* VT, const float* subg, float lam, float outscale, int unit, const int wave_s) {
;     const int tid_ = wave_s * 64 + lane_op();
;     const int tid = tid_, lane = tid & 63, wid = wave_s, q = lane & 31, hi = lane >> 5;
;     const int bh = unit >> 4, qb = unit & 15, b = bh >> 3, h = bh & 7, map = wid >> 2;
;     const int qrow0 = qb * 128 + 32 * (wid & 3);
;     const int td = qrow0 >> 6;
;     bf16x8 qf[4];
;     { const bf16_t* Qp = Q + (size_t)(b * SEQ + qrow0 + q) * DM + h * 128 + map * 64 + 8 * hi;
; #pragma unroll
;       for (int d0 = 0; d0 < 4; ++d0) qf[d0] = *(const bf16x8*)(Qp + 16 * d0); }
;     const float sl = __int_as_float(__builtin_amdgcn_readfirstlane(__float_as_int(exp2f(-(float)(h + 1)) * LOG2E)));
;     float sself;
;     { const bf16_t* Kp = Kg + (size_t)(b * SEQ + qrow0 + q) * DM + h * 128 + map * 64 + 8 * hi; float a = 0.f;
; #pragma unroll
;       for (int d0 = 0; d0 < 4; ++d0) { const u32x4 kv = *(const u32x4*)(Kp + 16 * d0); const u32x4 qv = __builtin_bit_cast(u32x4, qf[d0]);
; #pragma unroll
;           for (int j = 0; j < 4; ++j) a += bf_lo(kv[j]) * bf_lo(qv[j]) + bf_hi(kv[j]) * bf_hi(qv[j]); }
;       sself = swap_add(a); }
.LBB0_576:
	s_lshl_b32 s12, s61, 5
	s_add_i32 s16, s61, s39
	s_add_i32 s18, s12, s60
	s_and_b64 s[12:13], s[46:47], exec
	s_cselect_b32 s13, s18, s16
	s_cmpk_gt_i32 s13, 0x3ff
	s_cbranch_scc1 .LBB0_575
	v_mov_b32_e32 v0, v1
	s_lshl_b32 s12, s13, 7
	v_mbcnt_lo_u32_b32 v0, -1, v0
	s_and_b32 s12, s12, 0x780
	v_readlane_b32 s16, v253, 8
	s_lshl_b32 s18, s13, 4
	v_mbcnt_hi_u32_b32 v219, -1, v0
	s_or_b32 s12, s12, s16
	s_and_b32 s34, s18, 0xfffff800
	v_and_b32_e32 v3, 31, v219
	s_or_b32 s62, s12, s34
	v_or_b32_e32 v4, s62, v3
	v_ashrrev_i32_e32 v5, 31, v4
	s_bfe_u32 s19, s13, 0x30004
	v_lshlrev_b64 v[4:5], 11, v[4:5]
	v_lshl_add_u64 v[6:7], s[48:49], 0, v[4:5]
	s_lshl_b32 s16, s19, 8
	v_readlane_b32 s13, v253, 6
	v_lshl_add_u64 v[4:5], s[50:51], 0, v[4:5]
	v_bfe_u32 v2, v219, 5, 1
	s_lshl_b32 s20, s13, 1
	s_mov_b32 s21, s17
	v_lshl_add_u64 v[4:5], v[4:5], 0, s[16:17]
	v_lshl_add_u64 v[6:7], v[6:7], 0, s[16:17]
	v_lshlrev_b32_e32 v0, 4, v2
	v_lshl_add_u64 v[4:5], v[4:5], 0, s[20:21]
	v_lshl_add_u64 v[6:7], v[6:7], 0, s[20:21]
	v_lshl_add_u64 v[18:19], v[4:5], 0, v[0:1]
	v_lshl_add_u64 v[16:17], v[6:7], 0, v[0:1]
	global_load_dwordx4 v[4:7], v[18:19], off
	global_load_dwordx4 v[144:147], v[16:17], off
	global_load_dwordx4 v[8:11], v[18:19], off offset:32
	global_load_dwordx4 v[148:151], v[16:17], off offset:32
	global_load_dwordx4 v[12:15], v[18:19], off offset:64
	global_load_dwordx4 v[152:155], v[16:17], off offset:64
	global_load_dwordx4 v[156:159], v[16:17], off offset:96
	s_nop 0
	global_load_dwordx4 v[16:19], v[18:19], off offset:96
	s_add_i32 s13, s19, 1
	v_cvt_f32_ubyte0_e32 v0, s13
	s_mov_b32 s13, 0x42fc0000
	v_cmp_lt_f32_e32 vcc, s13, v0
	v_mov_b32_e32 v20, 0x42800000
	s_lshl_b32 s63, s19, 7
	v_cndmask_b32_e32 v20, 0, v20, vcc
	v_sub_f32_e32 v0, v20, v0
	v_exp_f32_e32 v0, v0
	s_and_b64 s[20:21], vcc, exec
	s_cselect_b32 s13, 0xffffffc0, 0
	v_bfe_u32 v216, v219, 4, 2
	v_ldexp_f32 v0, v0, s13
	v_bfe_u32 v218, v219, 3, 3
	v_readfirstlane_b32 s13, v0
	v_mov_b32_e32 v179, v1
	v_bitop3_b32 v217, v216, v219, 7 bitop3:0x78
	s_ashr_i32 s35, s34, 31
	v_mov_b32_e32 v171, v1
	v_mov_b32_e32 v173, v1
	s_mov_b64 s[20:21], 0x20000
	s_waitcnt vmcnt(7)
	v_lshlrev_b32_e32 v0, 16, v4
	v_and_b32_e32 v4, 0xffff0000, v4
	s_waitcnt vmcnt(6)
	v_and_b32_e32 v21, 0xffff0000, v144
	v_lshlrev_b32_e32 v20, 16, v144
	v_lshlrev_b32_e32 v22, 16, v5
	v_and_b32_e32 v5, 0xffff0000, v5
	v_and_b32_e32 v24, 0xffff0000, v145
	v_mul_f32_e32 v4, v21, v4
	v_lshlrev_b32_e32 v23, 16, v145
	v_lshlrev_b32_e32 v25, 16, v6
	v_and_b32_e32 v6, 0xffff0000, v6
	v_and_b32_e32 v27, 0xffff0000, v146
	v_mul_f32_e32 v5, v24, v5
	v_fmac_f32_e32 v4, v20, v0
	v_lshlrev_b32_e32 v26, 16, v146
	v_lshlrev_b32_e32 v28, 16, v7
	v_and_b32_e32 v7, 0xffff0000, v7
	v_and_b32_e32 v30, 0xffff0000, v147
	v_mul_f32_e32 v6, v27, v6
	v_fmac_f32_e32 v5, v23, v22
	v_add_f32_e32 v0, 0, v4
	v_lshlrev_b32_e32 v29, 16, v147
	s_waitcnt vmcnt(5)
	v_lshlrev_b32_e32 v31, 16, v8
	v_and_b32_e32 v8, 0xffff0000, v8
	s_waitcnt vmcnt(4)
	v_and_b32_e32 v33, 0xffff0000, v148
	v_mul_f32_e32 v7, v30, v7
	v_fmac_f32_e32 v6, v26, v25
	v_add_f32_e32 v0, v5, v0
	v_lshlrev_b32_e32 v32, 16, v148
	v_lshlrev_b32_e32 v34, 16, v9
	v_and_b32_e32 v9, 0xffff0000, v9
	v_and_b32_e32 v36, 0xffff0000, v149
	v_mul_f32_e32 v8, v33, v8
	v_fmac_f32_e32 v7, v29, v28
	v_add_f32_e32 v0, v6, v0
	v_lshlrev_b32_e32 v35, 16, v149
	v_lshlrev_b32_e32 v37, 16, v10
	v_and_b32_e32 v10, 0xffff0000, v10
	v_and_b32_e32 v39, 0xffff0000, v150
	v_mul_f32_e32 v9, v36, v9
	v_fmac_f32_e32 v8, v32, v31
	v_add_f32_e32 v0, v7, v0
	v_lshlrev_b32_e32 v38, 16, v150
	v_lshlrev_b32_e32 v40, 16, v11
	v_and_b32_e32 v11, 0xffff0000, v11
	v_and_b32_e32 v42, 0xffff0000, v151
	v_mul_f32_e32 v10, v39, v10
	v_fmac_f32_e32 v9, v35, v34
	v_add_f32_e32 v0, v8, v0
	v_lshlrev_b32_e32 v41, 16, v151
	v_mul_f32_e32 v11, v42, v11
	v_fmac_f32_e32 v10, v38, v37
	v_add_f32_e32 v0, v9, v0
	s_waitcnt vmcnt(3)
	v_and_b32_e32 v6, 0xffff0000, v12
	s_waitcnt vmcnt(2)
	v_and_b32_e32 v7, 0xffff0000, v152
	v_fmac_f32_e32 v11, v41, v40
	v_add_f32_e32 v0, v10, v0
	v_lshlrev_b32_e32 v4, 16, v12
	v_lshlrev_b32_e32 v5, 16, v152
	v_mul_f32_e32 v6, v7, v6
	v_add_f32_e32 v0, v11, v0
	v_fmac_f32_e32 v6, v5, v4
	v_add_f32_e32 v0, v6, v0
	v_and_b32_e32 v6, 0xffff0000, v13
	v_and_b32_e32 v7, 0xffff0000, v153
	v_lshlrev_b32_e32 v4, 16, v13
	v_lshlrev_b32_e32 v5, 16, v153
	v_mul_f32_e32 v6, v7, v6
	v_fmac_f32_e32 v6, v5, v4
	v_and_b32_e32 v9, 0xffff0000, v15
	v_and_b32_e32 v8, 0xffff0000, v14
	v_and_b32_e32 v11, 0xffff0000, v155
	v_and_b32_e32 v10, 0xffff0000, v154
	v_add_f32_e32 v0, v6, v0
	v_lshlrev_b32_e32 v5, 16, v15
	v_lshlrev_b32_e32 v4, 16, v14
	v_lshlrev_b32_e32 v7, 16, v155
	v_lshlrev_b32_e32 v6, 16, v154
	v_pk_mul_f32 v[8:9], v[10:11], v[8:9]
	s_waitcnt vmcnt(1)
	v_and_b32_e32 v11, 0xffff0000, v157
	v_pk_fma_f32 v[4:5], v[6:7], v[4:5], v[8:9]
	s_waitcnt vmcnt(0)
; __device__ __forceinline__ float swap_add(float v) { auto rr = __builtin_amdgcn_permlane32_swap(__float_as_uint(v), __float_as_uint(v), false, false); return __uint_as_float(rr[0]) + __uint_as_float(rr[1]); }
; #define AT_ISSUE_K(tt) do { const unsigned so_ = (unsigned)(((tt) & 3) * AT_SLOT); const bf16_t* kp_ = kgp + (size_t)(tt) * 64 * DM; \
;         glds16(kp_, (unsigned)__builtin_amdgcn_readfirstlane(kdst + so_)); glds16(kp_ + kx1, (unsigned)__builtin_amdgcn_readfirstlane(kdst + so_ + 1024)); } while (0)
; #define AT_ISSUE_V(tt) do { const unsigned so_ = (unsigned)(((tt) & 3) * AT_SLOT); const bf16_t* vp_ = vgp + (tt) * 64; \
;         glds16(vp_, (unsigned)__builtin_amdgcn_readfirstlane(vdst + so_)); glds16(vp_ + vx1, (unsigned)__builtin_amdgcn_readfirstlane(vdst + so_ + 1024)); } while (0)
; #define AT_BAR(N) asm volatile("s_waitcnt vmcnt(" #N ") lgkmcnt(0)\n\ts_barrier" ::: "memory")
; template <bool STORE> __device__ __forceinline__ void attn_unit(LAS unsigned char* lds, bf16_t* Q, const bf16_t* Kg, const bf16_t* VT, const float* subg, float lam, float outscale, int unit, const int wave_s) {
;     ...
;       sself = swap_add(a); }
;     const unsigned lds0 = (unsigned)(uintptr_t)lds;
;     const bf16_t* kgp; const bf16_t* vgp;
;     { const int kr = 8 * wid + (lane >> 4), kc = (lane & 15) ^ (kr & 15); kgp = Kg + (size_t)(b * SEQ + kr) * DM + h * 128 + kc * 8;
;       const int vr = 16 * wid + (lane >> 3), vc = (lane & 7) ^ ((vr >> 1) & 7); vgp = VT + (size_t)(h * 128 + vr) * T + b * SEQ + vc * 8; }
;     const int kx1 = ((((lane & 15) ^ ((8 * wid + (lane >> 4) + 4) & 15)) - ((lane & 15) ^ ((8 * wid + (lane >> 4)) & 15))) * 8) + 4 * DM;
;     const int vx1 = ((((lane & 7) ^ (((16 * wid + (lane >> 3) + 8) >> 1) & 7)) - ((lane & 7) ^ (((16 * wid + (lane >> 3)) >> 1) & 7))) * 8) + 8 * T;
;     const unsigned kdst = lds0 + wid * 2048, vdst = lds0 + AT_VOFF + wid * 2048;
;     ...
;     AT_ISSUE_K(0); AT_ISSUE_V(0); AT_ISSUE_K(1); AT_ISSUE_V(1); AT_ISSUE_K(2); AT_ISSUE_V(2); AT_ISSUE_K(3);
;     AT_BAR(8);
;     f32x16 o[4]; o[0] = f32x16{}; o[1] = f32x16{}; o[2] = f32x16{}; o[3] = f32x16{};
;     float mref = sself + 6.0f, lsum = 0.f;
;     const int koff = q * 256 + (((map * 8 + hi) ^ (q & 15)) << 4), voff = AT_VOFF + q * 128 + ((hi ^ ((q >> 1) & 7)) << 4);
;     const float qposf = (float)(qrow0 + q - 4 * hi);
;     f32x16 x0, x1, n0, n1;
	v_and_b32_e32 v9, 0xffff0000, v17
	v_add_f32_e32 v0, v4, v0
	v_and_b32_e32 v8, 0xffff0000, v16
	v_and_b32_e32 v10, 0xffff0000, v156
	v_add_f32_e32 v0, v5, v0
	v_lshlrev_b32_e32 v5, 16, v17
	v_lshlrev_b32_e32 v4, 16, v16
	v_lshlrev_b32_e32 v7, 16, v157
	v_lshlrev_b32_e32 v6, 16, v156
	v_pk_mul_f32 v[8:9], v[10:11], v[8:9]
	v_and_b32_e32 v11, 0xffff0000, v159
	v_pk_fma_f32 v[4:5], v[6:7], v[4:5], v[8:9]
	v_and_b32_e32 v9, 0xffff0000, v19
	v_add_f32_e32 v0, v4, v0
	v_and_b32_e32 v8, 0xffff0000, v18
	v_and_b32_e32 v10, 0xffff0000, v158
	v_add_f32_e32 v0, v5, v0
	v_lshlrev_b32_e32 v5, 16, v19
	v_lshlrev_b32_e32 v4, 16, v18
	v_lshlrev_b32_e32 v7, 16, v159
	v_lshlrev_b32_e32 v6, 16, v158
	v_pk_mul_f32 v[8:9], v[10:11], v[8:9]
	v_and_b32_e32 v11, 15, v219
	v_pk_fma_f32 v[4:5], v[6:7], v[4:5], v[8:9]
	v_and_b32_e32 v8, 7, v219
	v_add_f32_e32 v0, v4, v0
	v_add_f32_e32 v0, v5, v0
	v_mov_b32_e32 v4, 0x3fb8aa3b
	v_mul_f32_e32 v166, s13, v4
	v_mov_b32_e32 v4, v0
	s_nop 1
	v_permlane32_swap_b32_e32 v0, v4
	v_readlane_b32 s13, v253, 23
	v_add_f32_e32 v10, v0, v4
	v_add_f32_e32 v169, 0x40c00000, v10
	v_or_b32_e32 v0, s13, v216
	v_add_u32_e32 v4, s34, v0
	v_ashrrev_i32_e32 v5, 31, v4
	v_bitop3_b32 v6, v216, 11, s13 bitop3:0xc8
	v_lshlrev_b64 v[4:5], 11, v[4:5]
	v_readlane_b32 s13, v253, 29
	v_bitop3_b32 v7, v0, v11, 11 bitop3:0x6c
	v_lshl_add_u64 v[4:5], s[50:51], 0, v[4:5]
	s_add_i32 s19, s63, s13
	v_lshl_add_u64 v[4:5], v[4:5], 0, s[16:17]
	v_lshlrev_b32_e32 v178, 4, v7
	v_or_b32_e32 v0, s19, v218
	v_lshl_add_u64 v[180:181], v[4:5], 0, v[178:179]
	v_lshlrev_b64 v[4:5], 15, v[0:1]
	v_lshl_add_u64 v[4:5], s[52:53], 0, v[4:5]
	v_lshl_add_u64 v[4:5], s[34:35], 1, v[4:5]
	v_lshlrev_b32_e32 v0, 4, v217
	v_lshl_add_u64 v[182:183], v[4:5], 0, v[0:1]
	v_bitop3_b32 v0, v6, v11, 4 bitop3:0x36
	v_sub_u32_e32 v0, v0, v7
	v_mov_b32_e32 v4, 0x1000
	v_lshl_add_u32 v170, v0, 3, v4
	v_bitop3_b32 v0, v216, v8, 4 bitop3:0x36
	v_sub_u32_e32 v0, v0, v217
	v_mov_b32_e32 v4, 0x20000
	v_lshl_add_u32 v172, v0, 3, v4
	v_lshlrev_b64 v[4:5], 1, v[170:171]
	s_mov_b32 m0, s37
	s_nop 0
	global_load_lds_dwordx4 v[180:181], off
	v_lshl_add_u64 v[6:7], v[180:181], 0, v[4:5]
	s_add_i32 s13, s37, 0x400
	s_mov_b32 m0, s13
	s_nop 0
	global_load_lds_dwordx4 v[6:7], off
	v_lshlrev_b64 v[6:7], 1, v[172:173]
	s_mov_b32 m0, s3
	s_nop 0
	global_load_lds_dwordx4 v[182:183], off
	v_lshl_add_u64 v[8:9], v[182:183], 0, v[6:7]
	s_add_i32 s13, s37, 0x10400
	s_mov_b32 m0, s13
	s_nop 0
	global_load_lds_dwordx4 v[8:9], off
	v_lshl_add_u64 v[8:9], v[180:181], 0, s[20:21]
	s_add_i32 s13, s37, 0x4000
	s_mov_b32 m0, s13
	s_nop 0
	global_load_lds_dwordx4 v[8:9], off
	v_lshl_add_u64 v[8:9], v[8:9], 0, v[4:5]
	s_add_i32 s13, s37, 0x4400
	s_mov_b32 m0, s13
	s_nop 0
	global_load_lds_dwordx4 v[8:9], off
	v_lshl_add_u64 v[8:9], v[182:183], 0, s[22:23]
	s_add_i32 s13, s37, 0x14000
	s_mov_b32 m0, s13
	s_nop 0
	global_load_lds_dwordx4 v[8:9], off
	v_lshl_add_u64 v[8:9], v[8:9], 0, v[6:7]
	s_add_i32 s13, s37, 0x14400
	s_mov_b32 m0, s13
	s_nop 0
	global_load_lds_dwordx4 v[8:9], off
	v_lshl_add_u64 v[8:9], v[180:181], 0, s[26:27]
	s_add_i32 s13, s37, 0x8000
	s_mov_b32 m0, s13
	s_nop 0
	global_load_lds_dwordx4 v[8:9], off
	v_lshl_add_u64 v[8:9], v[8:9], 0, v[4:5]
	s_add_i32 s13, s37, 0x8400
	s_mov_b32 m0, s13
	s_nop 0
	global_load_lds_dwordx4 v[8:9], off
	v_lshl_add_u64 v[8:9], v[182:183], 0, s[24:25]
	s_add_i32 s13, s37, 0x18000
	s_mov_b32 m0, s13
	s_nop 0
	global_load_lds_dwordx4 v[8:9], off
	v_lshl_add_u64 v[6:7], v[8:9], 0, v[6:7]
	s_mov_b64 s[20:21], 0x60000
	s_add_i32 s13, s37, 0x18400
	s_mov_b32 m0, s13
	s_nop 0
	global_load_lds_dwordx4 v[6:7], off
	v_lshl_add_u64 v[6:7], v[180:181], 0, s[20:21]
	s_add_i32 s13, s37, 0xc000
	s_mov_b32 m0, s13
	s_nop 0
	global_load_lds_dwordx4 v[6:7], off
	v_lshl_add_u64 v[4:5], v[6:7], 0, v[4:5]
	s_add_i32 s13, s37, 0xc400
	s_mov_b32 m0, s13
	s_nop 0
	global_load_lds_dwordx4 v[4:5], off
	v_or_b32_e32 v0, s12, v3
	v_lshlrev_b32_e32 v4, 2, v2
	v_sub_u32_e32 v0, v0, v4
	s_cmp_gt_u32 s12, 63
	v_cvt_f32_i32_e32 v205, v0
	s_cselect_b64 s[40:41], -1, 0
	s_cmp_lt_u32 s12, 64
	s_cselect_b64 s[20:21], -1, 0
	v_cndmask_b32_e64 v4, 1.0, 0, s[20:21]
	v_mul_f32_e32 v4, v4, v166
	v_mul_f32_e64 v5, -v205, v4
	v_mov_b32_e32 v168, v4
	v_add_f32_e32 v6, v4, v168
	v_sub_f32_e32 v8, v4, v168
	v_sub_f32_e32 v9, v5, v169
	v_readlane_b32 s13, v253, 24
	v_mov_b32_e32 v7, v9
	s_waitcnt vmcnt(8) lgkmcnt(0)
	s_barrier
; #define AT_DIAG(tt, c0, c1) do { const float base_ = qposf - (float)(64 * (tt)); \
;         _Pragma("unroll") for (int r = 0; r < 16; ++r) { const float cr_ = (float)((r & 3) + 8 * (r >> 2)); c0[r] -= sl * fabsf(base_ - cr_); c1[r] -= sl * fabsf(base_ - 32.f - cr_); } } while (0)
; template <bool STORE> __device__ __forceinline__ void attn_unit(LAS unsigned char* lds, bf16_t* Q, const bf16_t* Kg, const bf16_t* VT, const float* subg, float lam, float outscale, int unit, const int wave_s) {
;     ...
;     { const float sg0 = td > 0 ? 1.f : 0.f;
;       AT_CINIT(0, sg0, x0, x1); AT_QK(0, x0, x1);
;       if (td == 0) AT_DIAG(0, x0, x1);
	v_mov_b32_e32 v96, v9
	v_bitop3_b32 v38, v2, v11, s13 bitop3:0x36
	v_add_f32_e32 v10, v6, v6
	v_add_f32_e32 v11, v7, v7
	s_and_b64 vcc, exec, s[40:41]
	v_pk_fma_f32 v[12:13], v[6:7], 2.0, v[10:11] op_sel_hi:[1,0,1]
	s_nop 0
	v_pk_fma_f32 v[10:11], v[10:11], 2.0, v[12:13] op_sel_hi:[1,0,1]
	v_mov_b32_e32 v19, v12
	v_pk_fma_f32 v[10:11], v[12:13], 2.0, v[10:11] op_sel_hi:[1,0,1]
	s_nop 0
	v_mov_b32_e32 v5, v10
	v_add_f32_e32 v10, v4, v6
	v_add_f32_e32 v11, v5, v7
	v_mov_b32_e32 v5, v6
	v_pk_mov_b32 v[16:17], v[10:11], v[12:13] op_sel:[1,0]
	v_mov_b32_e32 v18, v10
	v_add_f32_e32 v16, v16, v10
	v_add_f32_e32 v17, v17, v11
	v_add_f32_e32 v12, v18, v9
	v_add_f32_e32 v13, v19, v9
	v_add_f32_e32 v26, v18, v17
	v_add_f32_e32 v27, v19, v17
	v_add_f32_e32 v24, v18, v13
	v_add_f32_e32 v25, v19, v13
	v_add_f32_e32 v6, v4, v9
	v_add_f32_e32 v7, v5, v9
	v_add_f32_e32 v32, v18, v25
	v_add_f32_e32 v33, v19, v25
	v_add_f32_e32 v18, v18, v27
	v_add_f32_e32 v19, v19, v27
	v_add_f32_e32 v14, v4, v11
	v_add_f32_e32 v15, v5, v11
	v_add_f32_e32 v20, v4, v13
	v_add_f32_e32 v21, v5, v13
	v_add_f32_e32 v22, v4, v17
	v_add_f32_e32 v23, v5, v17
	v_add_f32_e32 v28, v4, v25
	v_add_f32_e32 v29, v5, v25
	v_add_f32_e32 v30, v4, v27
	v_add_f32_e32 v31, v5, v27
	v_add_f32_e32 v34, v4, v33
	v_add_f32_e32 v35, v5, v33
	v_mov_b32_e32 v99, v12
	v_mov_b32_e32 v100, v13
	v_add_f32_e32 v12, v4, v19
	v_add_f32_e32 v13, v5, v19
	v_lshlrev_b32_e32 v4, 8, v3
	v_lshl_add_u32 v210, v38, 4, v4
	v_add_u32_e32 v208, 0, v210
	v_mov_b32_e32 v97, v6
	v_mov_b32_e32 v98, v7
	ds_read_b128 v[4:7], v208
	v_add_f32_e32 v36, v10, v33
	v_add_f32_e32 v37, v11, v32
	v_xor_b32_e32 v211, 32, v210
	v_mov_b32_e32 v101, v20
	v_mov_b32_e32 v102, v21
	v_mov_b32_e32 v103, v24
	v_mov_b32_e32 v104, v25
	v_mov_b32_e32 v105, v28
	v_mov_b32_e32 v106, v29
	v_mov_b32_e32 v107, v32
	v_mov_b32_e32 v108, v33
	v_mov_b32_e32 v109, v34
	v_mov_b32_e32 v110, v35
	v_mov_b32_e32 v111, v36
	v_add_u32_e32 v209, 0, v211
	v_add_f32_e32 v20, v10, v19
	v_add_f32_e32 v21, v11, v18
	v_mov_b32_e32 v80, v11
	ds_read_b128 v[8:11], v208 offset:8192
	s_waitcnt lgkmcnt(1)
	v_mfma_f32_32x32x16_bf16 v[96:111], v[4:7], v[144:147], v[96:111]
	ds_read_b128 v[4:7], v209
	v_mov_b32_e32 v81, v14
	v_mov_b32_e32 v82, v15
	v_mov_b32_e32 v83, v16
	v_mov_b32_e32 v84, v17
	v_mov_b32_e32 v85, v22
	v_mov_b32_e32 v86, v23
	v_mov_b32_e32 v87, v26
	v_mov_b32_e32 v88, v27
	v_mov_b32_e32 v89, v30
	v_mov_b32_e32 v90, v31
	v_mov_b32_e32 v91, v18
	v_mov_b32_e32 v92, v19
	v_mov_b32_e32 v93, v12
	v_mov_b32_e32 v94, v13
	v_mov_b32_e32 v95, v20
	s_waitcnt lgkmcnt(0)
	v_mfma_f32_32x32x16_bf16 v[96:111], v[4:7], v[148:151], v[96:111]
	ds_read_b128 v[4:7], v209 offset:8192
	v_xor_b32_e32 v212, 64, v210
	v_add_u32_e32 v206, 0, v212
	v_xor_b32_e32 v213, 0x60, v210
	v_add_u32_e32 v207, 0, v213
	v_mfma_f32_32x32x16_bf16 v[80:95], v[8:11], v[144:147], v[80:95]
	s_waitcnt lgkmcnt(0)
	v_mfma_f32_32x32x16_bf16 v[80:95], v[4:7], v[148:151], v[80:95]
	ds_read_b128 v[4:7], v206
	s_waitcnt lgkmcnt(0)
	v_mfma_f32_32x32x16_bf16 v[96:111], v[4:7], v[152:155], v[96:111]
	ds_read_b128 v[4:7], v206 offset:8192
	s_waitcnt lgkmcnt(0)
	v_mfma_f32_32x32x16_bf16 v[80:95], v[4:7], v[152:155], v[80:95]
	ds_read_b128 v[4:7], v207
	s_waitcnt lgkmcnt(0)
	v_mfma_f32_32x32x16_bf16 v[96:111], v[4:7], v[156:159], v[96:111]
	ds_read_b128 v[4:7], v207 offset:8192
	s_waitcnt lgkmcnt(0)
	v_mfma_f32_32x32x16_bf16 v[80:95], v[4:7], v[156:159], v[80:95]
	s_cbranch_vccnz .LBB0_579
; #define AT_DIAG(tt, c0, c1) do { const float base_ = qposf - (float)(64 * (tt)); \
;         _Pragma("unroll") for (int r = 0; r < 16; ++r) { const float cr_ = (float)((r & 3) + 8 * (r >> 2)); c0[r] -= sl * fabsf(base_ - cr_); c1[r] -= sl * fabsf(base_ - 32.f - cr_); } } while (0)
; template <bool STORE> __device__ __forceinline__ void attn_unit(LAS unsigned char* lds, bf16_t* Q, const bf16_t* Kg, const bf16_t* VT, const float* subg, float lam, float outscale, int unit, const int wave_s) {
;     ...
;     { const float sg0 = td > 0 ? 1.f : 0.f;
;       AT_CINIT(0, sg0, x0, x1); AT_QK(0, x0, x1);
;       if (td == 0) AT_DIAG(0, x0, x1);
	v_add_u32_e32 v4, -1, v0
	v_cvt_f32_i32_e32 v5, v4
	v_add_u32_e32 v4, -3, v0
	v_cvt_f32_i32_e32 v7, v4
	v_add_u32_e32 v4, -9, v0
	v_cvt_f32_i32_e32 v9, v4
	v_add_u32_e32 v4, -11, v0
	v_cvt_f32_i32_e32 v11, v4
	v_add_u32_e32 v4, -16, v0
	v_cvt_f32_i32_e32 v14, v4
	v_subrev_u32_e32 v4, 19, v0
	v_subrev_u32_e32 v13, 18, v0
	v_cvt_f32_i32_e32 v16, v13
	v_cvt_f32_i32_e32 v15, v4
	v_subrev_u32_e32 v4, 25, v0
	v_subrev_u32_e32 v13, 24, v0
	v_add_u32_e32 v6, -2, v0
	v_add_u32_e32 v8, -8, v0
	v_add_u32_e32 v10, -10, v0
	v_subrev_u32_e32 v12, 17, v0
	v_cvt_f32_i32_e32 v18, v13
	v_cvt_f32_i32_e32 v17, v4
	v_subrev_u32_e32 v4, 27, v0
	v_subrev_u32_e32 v13, 26, v0
	v_cvt_f32_i32_e32 v6, v6
	v_cvt_f32_i32_e32 v8, v8
	v_cvt_f32_i32_e32 v10, v10
	v_cvt_f32_i32_e32 v12, v12
	v_cvt_f32_i32_e32 v20, v13
	v_cvt_f32_i32_e32 v19, v4
	v_and_b32_e32 v4, 0x7fffffff, v205
	v_and_b32_e32 v5, 0x7fffffff, v5
	v_and_b32_e32 v7, 0x7fffffff, v7
	v_and_b32_e32 v6, 0x7fffffff, v6
	v_and_b32_e32 v9, 0x7fffffff, v9
	v_and_b32_e32 v8, 0x7fffffff, v8
	v_and_b32_e32 v11, 0x7fffffff, v11
	v_and_b32_e32 v10, 0x7fffffff, v10
	v_and_b32_e32 v13, 0x7fffffff, v12
	v_and_b32_e32 v12, 0x7fffffff, v14
	v_and_b32_e32 v15, 0x7fffffff, v15
	v_and_b32_e32 v14, 0x7fffffff, v16
	v_and_b32_e32 v17, 0x7fffffff, v17
	v_and_b32_e32 v16, 0x7fffffff, v18
	v_and_b32_e32 v19, 0x7fffffff, v19
	v_and_b32_e32 v18, 0x7fffffff, v20
	v_pk_fma_f32 v[110:111], v[166:167], v[18:19], v[110:111] op_sel_hi:[0,1,1] neg_lo:[1,0,0] neg_hi:[1,0,0]
	v_pk_fma_f32 v[108:109], v[166:167], v[16:17], v[108:109] op_sel_hi:[0,1,1] neg_lo:[1,0,0] neg_hi:[1,0,0]
	v_pk_fma_f32 v[106:107], v[166:167], v[14:15], v[106:107] op_sel_hi:[0,1,1] neg_lo:[1,0,0] neg_hi:[1,0,0]
	v_pk_fma_f32 v[104:105], v[166:167], v[12:13], v[104:105] op_sel_hi:[0,1,1] neg_lo:[1,0,0] neg_hi:[1,0,0]
	v_pk_fma_f32 v[102:103], v[166:167], v[10:11], v[102:103] op_sel_hi:[0,1,1] neg_lo:[1,0,0] neg_hi:[1,0,0]
	v_pk_fma_f32 v[100:101], v[166:167], v[8:9], v[100:101] op_sel_hi:[0,1,1] neg_lo:[1,0,0] neg_hi:[1,0,0]
	v_pk_fma_f32 v[98:99], v[166:167], v[6:7], v[98:99] op_sel_hi:[0,1,1] neg_lo:[1,0,0] neg_hi:[1,0,0]
	v_pk_fma_f32 v[96:97], v[166:167], v[4:5], v[96:97] op_sel_hi:[0,1,1] neg_lo:[1,0,0] neg_hi:[1,0,0]
	v_subrev_u32_e32 v4, 33, v0
	v_subrev_u32_e32 v5, 32, v0
	v_subrev_u32_e32 v6, 35, v0
	v_subrev_u32_e32 v7, 34, v0
	v_subrev_u32_e32 v8, 41, v0
	v_subrev_u32_e32 v9, 40, v0
	v_subrev_u32_e32 v10, 43, v0
	v_subrev_u32_e32 v11, 42, v0
	v_subrev_u32_e32 v12, 49, v0
	v_subrev_u32_e32 v13, 48, v0
	v_subrev_u32_e32 v14, 51, v0
	v_subrev_u32_e32 v15, 50, v0
	v_subrev_u32_e32 v16, 57, v0
	v_subrev_u32_e32 v17, 56, v0
	v_subrev_u32_e32 v18, 59, v0
	v_subrev_u32_e32 v0, 58, v0
	v_cvt_f32_i32_e32 v0, v0
	v_cvt_f32_i32_e32 v18, v18
	v_cvt_f32_i32_e32 v19, v17
	v_cvt_f32_i32_e32 v16, v16
	v_cvt_f32_i32_e32 v17, v15
	v_cvt_f32_i32_e32 v14, v14
	v_cvt_f32_i32_e32 v15, v13
	v_cvt_f32_i32_e32 v12, v12
	v_cvt_f32_i32_e32 v13, v11
	v_cvt_f32_i32_e32 v10, v10
	v_cvt_f32_i32_e32 v11, v9
	v_cvt_f32_i32_e32 v8, v8
	v_cvt_f32_i32_e32 v4, v4
	v_cvt_f32_i32_e32 v9, v5
	v_cvt_f32_i32_e32 v6, v6
	v_cvt_f32_i32_e32 v20, v7
	v_and_b32_e32 v5, 0x7fffffff, v4
	v_and_b32_e32 v4, 0x7fffffff, v9
	v_and_b32_e32 v7, 0x7fffffff, v6
	v_and_b32_e32 v6, 0x7fffffff, v20
	v_and_b32_e32 v9, 0x7fffffff, v8
	v_and_b32_e32 v8, 0x7fffffff, v11
	v_and_b32_e32 v11, 0x7fffffff, v10
	v_and_b32_e32 v10, 0x7fffffff, v13
	v_and_b32_e32 v13, 0x7fffffff, v12
	v_and_b32_e32 v12, 0x7fffffff, v15
	v_and_b32_e32 v15, 0x7fffffff, v14
	v_and_b32_e32 v14, 0x7fffffff, v17
	v_and_b32_e32 v17, 0x7fffffff, v16
	v_and_b32_e32 v16, 0x7fffffff, v19
	v_and_b32_e32 v19, 0x7fffffff, v18
	v_and_b32_e32 v18, 0x7fffffff, v0
	v_pk_fma_f32 v[94:95], v[166:167], v[18:19], v[94:95] op_sel_hi:[0,1,1] neg_lo:[1,0,0] neg_hi:[1,0,0]
	v_pk_fma_f32 v[92:93], v[166:167], v[16:17], v[92:93] op_sel_hi:[0,1,1] neg_lo:[1,0,0] neg_hi:[1,0,0]
	v_pk_fma_f32 v[90:91], v[166:167], v[14:15], v[90:91] op_sel_hi:[0,1,1] neg_lo:[1,0,0] neg_hi:[1,0,0]
	v_pk_fma_f32 v[88:89], v[166:167], v[12:13], v[88:89] op_sel_hi:[0,1,1] neg_lo:[1,0,0] neg_hi:[1,0,0]
	v_pk_fma_f32 v[86:87], v[166:167], v[10:11], v[86:87] op_sel_hi:[0,1,1] neg_lo:[1,0,0] neg_hi:[1,0,0]
	v_pk_fma_f32 v[84:85], v[166:167], v[8:9], v[84:85] op_sel_hi:[0,1,1] neg_lo:[1,0,0] neg_hi:[1,0,0]
	v_pk_fma_f32 v[82:83], v[166:167], v[6:7], v[82:83] op_sel_hi:[0,1,1] neg_lo:[1,0,0] neg_hi:[1,0,0]
	v_pk_fma_f32 v[80:81], v[166:167], v[4:5], v[80:81] op_sel_hi:[0,1,1] neg_lo:[1,0,0] neg_hi:[1,0,0]

.LBB0_583:
	s_cmp_gt_u32 s20, 27
	s_cselect_b64 s[12:13], -1, 0
	s_mov_b64 s[42:43], -1
	s_and_b64 vcc, exec, s[12:13]
	s_cbranch_vccz .LBB0_587
	s_cmp_lg_u32 s21, 0x84000
	s_cbranch_scc1 .LBB0_586
	s_add_i32 s30, s37, 0x1c000
	s_mov_b32 m0, s30
	s_nop 0
	global_load_lds_dwordx4 v[174:175], off
	s_add_i32 s30, s37, 0x1c400
	s_mov_b32 m0, s30
	s_nop 0
	global_load_lds_dwordx4 v[176:177], off

.LBB0_587:
	s_andn2_b64 vcc, exec, s[42:43]
	v_lshl_add_u64 v[4:5], s[10:11], 0, v[188:189]
	v_lshl_add_u64 v[2:3], s[10:11], 0, v[190:191]
	s_cbranch_vccnz .LBB0_589
	s_add_i32 s30, s21, 0xfffec000
	s_and_b32 s30, s30, 0x8000
	s_add_i32 s30, s30, s37
	v_lshl_add_u64 v[6:7], v[4:5], 0, s[56:57]
	s_mov_b32 m0, s30
	s_nop 0
	global_load_lds_dwordx4 v[6:7], off
	s_addk_i32 s30, 0x400
	v_lshl_add_u64 v[6:7], v[170:171], 1, v[6:7]
	s_mov_b32 m0, s30
	s_nop 0
	global_load_lds_dwordx4 v[6:7], off
	s_add_i32 s30, s21, 0xffff8000
	s_and_b32 s30, s30, 0xc000
	v_lshl_add_u64 v[6:7], v[2:3], 0, s[74:75]
	s_add_i32 s30, s30, s3
	s_mov_b32 m0, s30
	s_nop 0
	global_load_lds_dwordx4 v[6:7], off
	v_lshl_add_u64 v[6:7], v[172:173], 1, v[6:7]
	s_addk_i32 s30, 0x400
	s_mov_b32 m0, s30
	s_nop 0
	global_load_lds_dwordx4 v[6:7], off
.LBB0_589:
	s_add_i32 s30, s21, 0xffff0000
	s_and_b32 s30, s30, 0xc000
	s_add_i32 s42, s30, 0
	v_add_u32_e32 v0, s42, v210
	s_sub_i32 s43, s28, 64
	ds_read_b128 v[6:9], v0
	ds_read_b128 v[10:13], v0 offset:8192
	v_cvt_f32_u32_e32 v0, s43
	v_add_u32_e32 v14, s42, v211
	ds_read_b128 v[224:227], v14
	ds_read_b128 v[228:231], v14 offset:8192
	s_add_i32 s36, s21, 0xfffec000
	v_sub_f32_e32 v0, v0, v205
	v_fma_f32 v112, v166, v0, -v169
	v_add_f32_e32 v128, v168, v112
	v_add_f32_e32 v118, v186, v128
	v_add_f32_e32 v119, v187, v128
	v_add_f32_e32 v116, v186, v112
	v_add_f32_e32 v117, v187, v112
	v_add_f32_e32 v126, v186, v119
	v_add_f32_e32 v127, v187, v119
	v_add_f32_e32 v114, v166, v128
	v_add_f32_e32 v115, v167, v128
	v_add_f32_e32 v140, v186, v127
	v_add_f32_e32 v141, v187, v127
	v_add_f32_e32 v122, v166, v119
	v_add_f32_e32 v123, v167, v119
	v_add_f32_e32 v124, v186, v117
	v_add_f32_e32 v125, v187, v117
	v_add_f32_e32 v138, v166, v127
	v_add_f32_e32 v139, v167, v127
	v_add_f32_e32 v142, v166, v141
	v_add_f32_e32 v143, v167, v141
	v_add_f32_e32 v240, v186, v141
	v_add_f32_e32 v120, v166, v117
	v_add_f32_e32 v121, v167, v117
	v_add_f32_e32 v234, v186, v125
	v_add_f32_e32 v235, v187, v125
	v_mov_b32_e32 v129, v114
	v_mov_b32_e32 v130, v115
	v_mov_b32_e32 v131, v118
	v_mov_b32_e32 v132, v119
	v_mov_b32_e32 v133, v122
	v_mov_b32_e32 v134, v123
	v_mov_b32_e32 v135, v126
	v_mov_b32_e32 v136, v127
	v_mov_b32_e32 v137, v138
	v_mov_b32_e32 v138, v139
	v_mov_b32_e32 v139, v140
	v_mov_b32_e32 v140, v141
	v_mov_b32_e32 v141, v142
	v_mov_b32_e32 v142, v143
	v_mov_b32_e32 v143, v240
	v_add_f32_e32 v14, v166, v112
	v_add_f32_e32 v15, v167, v112
	v_add_f32_e32 v232, v166, v125
	v_add_f32_e32 v233, v167, v125
	v_add_f32_e32 v236, v166, v235
	v_add_f32_e32 v237, v167, v235
	v_add_f32_e32 v238, v186, v235
	v_mov_b32_e32 v113, v14
	v_mov_b32_e32 v114, v15
	v_mov_b32_e32 v115, v116
	v_mov_b32_e32 v116, v117
	v_mov_b32_e32 v117, v120
	v_mov_b32_e32 v118, v121
	v_mov_b32_e32 v119, v124
	v_mov_b32_e32 v120, v125
	v_mov_b32_e32 v121, v232
	v_mov_b32_e32 v122, v233
	v_mov_b32_e32 v123, v234
	v_mov_b32_e32 v124, v235
	v_mov_b32_e32 v125, v236
	v_mov_b32_e32 v126, v237
	v_mov_b32_e32 v127, v238
	s_waitcnt lgkmcnt(2)
	v_mfma_f32_32x32x16_bf16 v[128:143], v[10:13], v[144:147], v[128:143]
	v_add_u32_e32 v0, s42, v212
	s_and_b32 s36, s36, 0x8000
	v_exp_f32_e32 v96, v96
	v_exp_f32_e32 v14, v97
	v_exp_f32_e32 v80, v80
	v_exp_f32_e32 v98, v98
	v_exp_f32_e32 v82, v82
	v_mfma_f32_32x32x16_bf16 v[112:127], v[6:9], v[144:147], v[112:127]
	ds_read_b128 v[6:9], v0
	ds_read_b128 v[10:13], v0 offset:8192
	v_add_u32_e32 v0, s42, v213
	v_exp_f32_e32 v248, v99
	v_exp_f32_e32 v250, v83
	v_exp_f32_e32 v83, v84
	v_exp_f32_e32 v84, v86
	v_exp_f32_e32 v196, v103
	s_waitcnt lgkmcnt(3)
	v_mfma_f32_32x32x16_bf16 v[112:127], v[224:227], v[148:151], v[112:127]
	ds_read_b128 v[224:227], v0
	ds_read_b128 v[232:235], v0 offset:8192
	v_add_u32_e32 v0, s36, v204
	ds_read_b128 v[236:239], v0
	ds_read_b128 v[240:243], v0 offset:4096
	v_exp_f32_e32 v86, v106
	v_exp_f32_e32 v198, v105
	v_exp_f32_e32 v106, v89
	v_exp_f32_e32 v164, v107
	s_waitcnt lgkmcnt(6)
	v_mfma_f32_32x32x16_bf16 v[128:143], v[228:231], v[148:151], v[128:143]
	ds_read_b128 v[228:231], v0 offset:8192
	ds_read_b128 v[244:247], v0 offset:12288
	v_exp_f32_e32 v0, v81
	v_exp_f32_e32 v81, v104
	v_exp_f32_e32 v104, v87
	v_exp_f32_e32 v87, v90
	v_exp_f32_e32 v160, v91
	v_exp_f32_e32 v89, v92
	s_waitcnt lgkmcnt(7)
	v_mfma_f32_32x32x16_bf16 v[112:127], v[6:9], v[152:155], v[112:127]
	v_exp_f32_e32 v8, v100
	v_exp_f32_e32 v9, v102
	v_exp_f32_e32 v90, v110
	v_exp_f32_e32 v91, v94
	v_exp_f32_e32 v162, v109
	v_exp_f32_e32 v200, v111
	v_exp_f32_e32 v110, v95
	s_waitcnt lgkmcnt(6)
	v_mfma_f32_32x32x16_bf16 v[128:143], v[10:13], v[152:155], v[128:143]
	v_cvt_pk_bf16_f32 v6, v96, v14
	v_add_f32_e32 v15, v96, v80
	v_add_f32_e32 v249, v98, v82
	v_add_f32_e32 v197, v9, v84
	v_add_f32_e32 v165, v86, v87
	v_add_f32_e32 v201, v90, v91
	v_cvt_pk_bf16_f32 v7, v98, v248
	s_waitcnt lgkmcnt(5)
	v_mfma_f32_32x32x16_bf16 v[112:127], v[224:227], v[156:159], v[112:127]
	v_exp_f32_e32 v224, v101
	v_exp_f32_e32 v226, v85
	v_exp_f32_e32 v85, v88
	v_exp_f32_e32 v88, v108
	v_exp_f32_e32 v108, v93
	v_add_f32_e32 v225, v8, v83
	v_add_f32_e32 v199, v81, v85
	s_waitcnt lgkmcnt(4)
	v_mfma_f32_32x32x16_bf16 v[128:143], v[232:235], v[156:159], v[128:143]
	v_add_f32_e32 v163, v88, v89
	v_cvt_pk_bf16_f32 v8, v8, v224
	v_cvt_pk_bf16_f32 v9, v9, v196
	v_cvt_pk_bf16_f32 v10, v81, v198
	v_cvt_pk_bf16_f32 v11, v86, v164
	v_cvt_pk_bf16_f32 v12, v88, v162
	v_cvt_pk_bf16_f32 v13, v90, v200
	v_cvt_pk_bf16_f32 v80, v80, v0
	v_cvt_pk_bf16_f32 v81, v82, v250
	v_cvt_pk_bf16_f32 v82, v83, v226
	v_cvt_pk_bf16_f32 v83, v84, v104
	v_cvt_pk_bf16_f32 v84, v85, v106
	v_cvt_pk_bf16_f32 v85, v87, v160
	v_cvt_pk_bf16_f32 v86, v89, v108
	v_cvt_pk_bf16_f32 v87, v91, v110
	v_add_f32_e32 v14, v14, v0
	v_add_f32_e32 v15, v15, v1
	v_add_u32_e32 v100, s36, v220
	v_add_f32_e32 v251, v14, v15
	v_add_f32_e32 v14, v248, v250
	v_add_f32_e32 v15, v249, v251
	s_waitcnt lgkmcnt(3)
	v_mfma_f32_32x32x16_bf16 v[64:79], v[236:239], v[6:9], v[64:79]
	v_add_f32_e32 v227, v14, v15
	v_add_f32_e32 v14, v224, v226
	v_add_f32_e32 v15, v225, v227
	ds_read_b128 v[88:91], v100
	ds_read_b128 v[92:95], v100 offset:4096
	ds_read_b128 v[96:99], v100 offset:8192
	ds_read_b128 v[100:103], v100 offset:12288
	v_add_f32_e32 v105, v14, v15
	v_add_f32_e32 v14, v196, v104
	v_add_f32_e32 v15, v197, v105
	s_waitcnt lgkmcnt(6)
	v_mfma_f32_32x32x16_bf16 v[48:63], v[240:243], v[6:9], v[48:63]
	v_add_f32_e32 v107, v14, v15
	v_add_f32_e32 v14, v198, v106
	v_add_f32_e32 v15, v199, v107
	s_nop 0
	v_add_f32_e32 v161, v14, v15
	v_add_f32_e32 v14, v164, v160
	v_add_f32_e32 v15, v165, v161
	s_waitcnt lgkmcnt(5)
	v_mfma_f32_32x32x16_bf16 v[32:47], v[228:231], v[6:9], v[32:47]
	v_add_f32_e32 v109, v14, v15
	v_add_f32_e32 v14, v162, v108
	v_add_f32_e32 v15, v163, v109
	s_nop 0
	v_add_f32_e32 v111, v14, v15
	v_add_f32_e32 v14, v200, v110
	v_add_f32_e32 v15, v201, v111
	s_waitcnt lgkmcnt(4)
	v_mfma_f32_32x32x16_bf16 v[16:31], v[244:247], v[6:9], v[16:31]
	v_add_f32_e32 v0, v14, v15
	v_add_f32_e32 v6, v184, v0
	s_waitcnt lgkmcnt(3)
	v_mfma_f32_32x32x16_bf16 v[64:79], v[88:91], v[10:13], v[64:79]
	v_add_u32_e32 v0, s36, v221
	s_waitcnt lgkmcnt(2)
	v_mfma_f32_32x32x16_bf16 v[48:63], v[92:95], v[10:13], v[48:63]
	s_waitcnt lgkmcnt(1)
	v_mfma_f32_32x32x16_bf16 v[32:47], v[96:99], v[10:13], v[32:47]
	ds_read_b128 v[88:91], v0
	ds_read_b128 v[92:95], v0 offset:4096
	ds_read_b128 v[96:99], v0 offset:8192
	ds_read_b128 v[104:107], v0 offset:12288
	s_waitcnt lgkmcnt(4)
	v_mfma_f32_32x32x16_bf16 v[16:31], v[100:103], v[10:13], v[16:31]
	v_add_u32_e32 v0, s36, v222
	ds_read_b128 v[8:11], v0
	ds_read_b128 v[12:15], v0 offset:4096
	s_waitcnt lgkmcnt(5)
	v_mfma_f32_32x32x16_bf16 v[64:79], v[88:91], v[80:83], v[64:79]
	ds_read_b128 v[88:91], v0 offset:8192
	ds_read_b128 v[100:103], v0 offset:12288
	v_max_f32_e32 v0, v113, v113
	v_max_f32_e32 v7, v129, v129
	v_max_f32_e32 v0, v0, v7
	v_max3_f32 v7, v112, v128, v114
	v_max3_f32 v0, v0, v115, v131
	v_max3_f32 v7, v7, v130, v116
	v_max3_f32 v0, v0, v117, v133
	s_waitcnt lgkmcnt(6)
	v_mfma_f32_32x32x16_bf16 v[48:63], v[92:95], v[80:83], v[48:63]
	v_max3_f32 v7, v7, v132, v118
	v_max3_f32 v0, v0, v119, v135
	v_max3_f32 v7, v7, v134, v120
	v_max3_f32 v0, v0, v121, v137
	v_max3_f32 v7, v7, v136, v122
	v_max3_f32 v0, v0, v123, v139
	v_max3_f32 v7, v7, v138, v124
	s_waitcnt lgkmcnt(5)
	v_mfma_f32_32x32x16_bf16 v[32:47], v[96:99], v[80:83], v[32:47]
	v_max3_f32 v0, v0, v125, v141
	v_max3_f32 v7, v7, v140, v126
	v_max3_f32 v0, v0, v127, v143
	v_max3_f32 v0, v7, v142, v0
	v_mov_b32_e32 v7, v0
	s_nop 1
	v_permlane32_swap_b32_e32 v0, v7
	s_waitcnt lgkmcnt(4)
	v_mfma_f32_32x32x16_bf16 v[16:31], v[104:107], v[80:83], v[16:31]
	s_waitcnt lgkmcnt(3)
	v_mfma_f32_32x32x16_bf16 v[64:79], v[8:11], v[84:87], v[64:79]
	v_max_f32_e32 v7, v7, v7
	v_max_f32_e32 v0, v0, v0
	v_max_f32_e32 v0, v0, v7
	v_cmp_lt_f32_e32 vcc, s93, v0
	s_waitcnt lgkmcnt(2)
	v_mfma_f32_32x32x16_bf16 v[48:63], v[12:15], v[84:87], v[48:63]
	s_waitcnt lgkmcnt(1)
	v_mfma_f32_32x32x16_bf16 v[32:47], v[88:91], v[84:87], v[32:47]
	s_waitcnt lgkmcnt(0)
	v_mfma_f32_32x32x16_bf16 v[16:31], v[100:103], v[84:87], v[16:31]
	s_cbranch_vccz .LBB0_591
	v_max_f32_e32 v0, v0, v0
	v_max_f32_e32 v7, 0, v0
	v_exp_f32_e64 v0, -v7
	v_add_f32_e32 v169, v169, v7
	v_sub_f32_e32 v127, v127, v7
	v_sub_f32_e32 v126, v126, v7
	v_pk_mul_f32 v[78:79], v[78:79], v[0:1] op_sel_hi:[1,0]
	v_pk_mul_f32 v[76:77], v[76:77], v[0:1] op_sel_hi:[1,0]
	v_pk_mul_f32 v[74:75], v[74:75], v[0:1] op_sel_hi:[1,0]
	v_pk_mul_f32 v[72:73], v[72:73], v[0:1] op_sel_hi:[1,0]
	v_pk_mul_f32 v[70:71], v[70:71], v[0:1] op_sel_hi:[1,0]
	v_pk_mul_f32 v[68:69], v[68:69], v[0:1] op_sel_hi:[1,0]
	v_pk_mul_f32 v[66:67], v[66:67], v[0:1] op_sel_hi:[1,0]
	v_pk_mul_f32 v[64:65], v[64:65], v[0:1] op_sel_hi:[1,0]
	v_pk_mul_f32 v[62:63], v[62:63], v[0:1] op_sel_hi:[1,0]
	v_pk_mul_f32 v[60:61], v[60:61], v[0:1] op_sel_hi:[1,0]
	v_pk_mul_f32 v[58:59], v[58:59], v[0:1] op_sel_hi:[1,0]
	v_pk_mul_f32 v[56:57], v[56:57], v[0:1] op_sel_hi:[1,0]
	v_pk_mul_f32 v[54:55], v[54:55], v[0:1] op_sel_hi:[1,0]
	v_pk_mul_f32 v[52:53], v[52:53], v[0:1] op_sel_hi:[1,0]
	v_pk_mul_f32 v[50:51], v[50:51], v[0:1] op_sel_hi:[1,0]
	v_pk_mul_f32 v[48:49], v[48:49], v[0:1] op_sel_hi:[1,0]
	v_pk_mul_f32 v[46:47], v[0:1], v[46:47] op_sel_hi:[0,1]
	v_pk_mul_f32 v[44:45], v[0:1], v[44:45] op_sel_hi:[0,1]
	v_pk_mul_f32 v[42:43], v[0:1], v[42:43] op_sel_hi:[0,1]
	v_pk_mul_f32 v[40:41], v[0:1], v[40:41] op_sel_hi:[0,1]
	v_pk_mul_f32 v[38:39], v[0:1], v[38:39] op_sel_hi:[0,1]
	v_pk_mul_f32 v[36:37], v[0:1], v[36:37] op_sel_hi:[0,1]
	v_pk_mul_f32 v[34:35], v[0:1], v[34:35] op_sel_hi:[0,1]
	v_pk_mul_f32 v[32:33], v[0:1], v[32:33] op_sel_hi:[0,1]
	v_pk_mul_f32 v[30:31], v[0:1], v[30:31] op_sel_hi:[0,1]
	v_pk_mul_f32 v[28:29], v[0:1], v[28:29] op_sel_hi:[0,1]
	v_pk_mul_f32 v[26:27], v[0:1], v[26:27] op_sel_hi:[0,1]
	v_pk_mul_f32 v[24:25], v[0:1], v[24:25] op_sel_hi:[0,1]
	v_pk_mul_f32 v[22:23], v[0:1], v[22:23] op_sel_hi:[0,1]
	v_pk_mul_f32 v[20:21], v[0:1], v[20:21] op_sel_hi:[0,1]
	v_pk_mul_f32 v[18:19], v[0:1], v[18:19] op_sel_hi:[0,1]
	v_pk_mul_f32 v[16:17], v[0:1], v[16:17] op_sel_hi:[0,1]
	v_sub_f32_e32 v125, v125, v7
	v_sub_f32_e32 v124, v124, v7
	v_sub_f32_e32 v123, v123, v7
	v_sub_f32_e32 v122, v122, v7
	v_sub_f32_e32 v121, v121, v7
	v_sub_f32_e32 v120, v120, v7
	v_sub_f32_e32 v119, v119, v7
	v_sub_f32_e32 v118, v118, v7
	v_sub_f32_e32 v117, v117, v7
	v_sub_f32_e32 v116, v116, v7
	v_sub_f32_e32 v115, v115, v7
	v_sub_f32_e32 v114, v114, v7
	v_sub_f32_e32 v113, v113, v7
	v_sub_f32_e32 v112, v112, v7
	v_sub_f32_e32 v143, v143, v7
	v_sub_f32_e32 v142, v142, v7
	v_sub_f32_e32 v141, v141, v7
	v_sub_f32_e32 v140, v140, v7
	v_sub_f32_e32 v139, v139, v7
	v_sub_f32_e32 v138, v138, v7
	v_sub_f32_e32 v137, v137, v7
	v_sub_f32_e32 v136, v136, v7
	v_sub_f32_e32 v135, v135, v7
	v_sub_f32_e32 v134, v134, v7
	v_sub_f32_e32 v133, v133, v7
	v_sub_f32_e32 v132, v132, v7
	v_sub_f32_e32 v131, v131, v7
	v_sub_f32_e32 v130, v130, v7
	v_sub_f32_e32 v129, v129, v7
	v_sub_f32_e32 v128, v128, v7
	v_mul_f32_e32 v6, v6, v0

.LBB0_594:
	s_and_b32 s42, s21, 0xc000
	s_mov_b64 s[54:55], 0x8da0000
	v_lshl_add_u64 v[4:5], v[4:5], 0, s[54:55]
	s_add_i32 s42, s42, s37
	s_mov_b32 m0, s42
	s_nop 0
	global_load_lds_dwordx4 v[4:5], off
	v_lshl_add_u64 v[4:5], v[170:171], 1, v[4:5]
	s_addk_i32 s42, 0x400
	s_mov_b32 m0, s42
	s_nop 0
	global_load_lds_dwordx4 v[4:5], off
	v_lshl_add_u64 v[2:3], v[2:3], 0, s[88:89]
	s_add_i32 s36, s36, s3
	s_mov_b32 m0, s36
	s_nop 0
	global_load_lds_dwordx4 v[2:3], off
	v_lshl_add_u64 v[2:3], v[172:173], 1, v[2:3]
	s_addk_i32 s36, 0x400
	s_mov_b32 m0, s36
	s_nop 0
	global_load_lds_dwordx4 v[2:3], off
.LBB0_595:
	s_add_i32 s36, s21, 0xffff4000
	s_and_b32 s36, s36, 0x8000
	s_add_i32 s36, s36, 0
	v_add_u32_e32 v0, s36, v210
	ds_read_b128 v[2:5], v0
	ds_read_b128 v[8:11], v0 offset:8192
	v_cvt_f32_u32_e32 v0, s28
	v_add_u32_e32 v7, s36, v211
	ds_read_b128 v[12:15], v7
	ds_read_b128 v[224:227], v7 offset:8192
	v_sub_f32_e32 v0, v0, v205
	v_fma_f32 v96, v166, v0, -v169
	v_add_f32_e32 v80, v168, v96
	v_add_f32_e32 v86, v186, v96
	v_add_f32_e32 v87, v187, v96
	v_add_f32_e32 v88, v186, v80
	v_add_f32_e32 v89, v187, v80
	v_add_f32_e32 v94, v186, v87
	v_add_f32_e32 v95, v187, v87
	v_add_f32_e32 v160, v186, v89
	v_add_f32_e32 v161, v187, v89
	v_add_f32_e32 v108, v186, v95
	v_add_f32_e32 v109, v187, v95
	v_add_f32_e32 v82, v166, v96
	v_add_f32_e32 v83, v167, v96
	v_add_f32_e32 v90, v166, v87
	v_add_f32_e32 v91, v167, v87
	v_add_f32_e32 v106, v166, v95
	v_add_f32_e32 v107, v167, v95
	v_add_f32_e32 v164, v186, v161
	v_add_f32_e32 v165, v187, v161
	v_add_f32_e32 v110, v166, v109
	v_add_f32_e32 v111, v167, v109
	v_add_f32_e32 v196, v186, v109
	v_add_f32_e32 v84, v166, v80
	v_add_f32_e32 v85, v167, v80
	v_add_f32_e32 v92, v166, v89
	v_add_f32_e32 v93, v167, v89
	v_mov_b32_e32 v97, v82
	v_mov_b32_e32 v98, v83
	v_mov_b32_e32 v99, v86
	v_mov_b32_e32 v100, v87
	v_mov_b32_e32 v101, v90
	v_mov_b32_e32 v102, v91
	v_mov_b32_e32 v103, v94
	v_mov_b32_e32 v104, v95
	v_mov_b32_e32 v105, v106
	v_mov_b32_e32 v106, v107
	v_mov_b32_e32 v107, v108
	v_mov_b32_e32 v108, v109
	v_mov_b32_e32 v109, v110
	v_mov_b32_e32 v110, v111
	v_mov_b32_e32 v111, v196
	v_add_f32_e32 v94, v166, v165
	v_add_f32_e32 v95, v167, v165
	v_add_f32_e32 v162, v166, v161
	v_add_f32_e32 v163, v167, v161
	v_add_f32_e32 v196, v186, v165
	v_mov_b32_e32 v81, v84
	v_mov_b32_e32 v82, v85
	v_mov_b32_e32 v83, v88
	v_mov_b32_e32 v84, v89
	v_mov_b32_e32 v85, v92
	v_mov_b32_e32 v86, v93
	v_mov_b32_e32 v87, v160
	v_mov_b32_e32 v88, v161
	v_mov_b32_e32 v89, v162
	v_mov_b32_e32 v90, v163
	v_mov_b32_e32 v91, v164
	v_mov_b32_e32 v92, v165
	v_mov_b32_e32 v93, v94
	v_mov_b32_e32 v94, v95
	v_mov_b32_e32 v95, v196
	s_waitcnt lgkmcnt(3)
	v_mfma_f32_32x32x16_bf16 v[96:111], v[2:5], v[144:147], v[96:111]
	v_add_u32_e32 v0, s36, v212
	v_exp_f32_e32 v7, v112
	v_exp_f32_e32 v112, v128
	v_exp_f32_e32 v160, v129
	v_exp_f32_e32 v116, v116
	v_exp_f32_e32 v128, v132
	v_exp_f32_e32 v132, v115
	s_waitcnt lgkmcnt(2)
	v_mfma_f32_32x32x16_bf16 v[80:95], v[8:11], v[144:147], v[80:95]
	ds_read_b128 v[2:5], v0
	ds_read_b128 v[8:11], v0 offset:8192
	v_add_u32_e32 v0, s36, v213
	v_exp_f32_e32 v162, v131
	v_exp_f32_e32 v115, v134
	v_exp_f32_e32 v134, v117
	v_exp_f32_e32 v164, v133
	v_exp_f32_e32 v198, v119
	s_waitcnt lgkmcnt(3)
	v_mfma_f32_32x32x16_bf16 v[96:111], v[12:15], v[148:151], v[96:111]
	ds_read_b128 v[12:15], v0
	ds_read_b128 v[228:231], v0 offset:8192
	v_add_u32_e32 v0, s30, v204
	ds_read_b128 v[232:235], v0
	ds_read_b128 v[236:239], v0 offset:4096
	v_exp_f32_e32 v117, v136
	v_exp_f32_e32 v196, v135
	v_exp_f32_e32 v136, v121
	v_exp_f32_e32 v200, v137
	s_waitcnt lgkmcnt(6)
	v_mfma_f32_32x32x16_bf16 v[80:95], v[224:227], v[148:151], v[80:95]
	ds_read_b128 v[224:227], v0 offset:8192
	ds_read_b128 v[240:243], v0 offset:12288
	v_exp_f32_e32 v0, v113
	v_exp_f32_e32 v113, v114
	v_exp_f32_e32 v114, v130
	v_exp_f32_e32 v244, v139
	v_exp_f32_e32 v119, v140
	v_exp_f32_e32 v140, v125
	s_waitcnt lgkmcnt(7)
	v_mfma_f32_32x32x16_bf16 v[96:111], v[2:5], v[152:155], v[96:111]
	v_exp_f32_e32 v5, v118
	v_exp_f32_e32 v118, v138
	v_exp_f32_e32 v138, v123
	v_exp_f32_e32 v246, v141
	v_exp_f32_e32 v248, v143
	v_add_f32_e32 v161, v112, v7
	v_add_f32_e32 v163, v114, v113
	s_waitcnt lgkmcnt(6)
	v_mfma_f32_32x32x16_bf16 v[80:95], v[8:11], v[152:155], v[80:95]
	v_add_f32_e32 v165, v128, v116
	v_add_f32_e32 v197, v115, v5
	v_cvt_pk_bf16_f32 v2, v7, v0
	v_cvt_pk_bf16_f32 v3, v113, v132
	v_cvt_pk_bf16_f32 v4, v116, v134
	v_cvt_pk_bf16_f32 v5, v5, v198
	v_cvt_pk_bf16_f32 v113, v118, v244
	s_waitcnt lgkmcnt(5)
	v_mfma_f32_32x32x16_bf16 v[96:111], v[12:15], v[156:159], v[96:111]
	v_exp_f32_e32 v12, v120
	v_exp_f32_e32 v13, v122
	v_exp_f32_e32 v14, v124
	v_exp_f32_e32 v15, v126
	v_exp_f32_e32 v120, v142
	v_exp_f32_e32 v142, v127
	v_add_f32_e32 v201, v117, v12
	s_waitcnt lgkmcnt(4)
	v_mfma_f32_32x32x16_bf16 v[80:95], v[228:231], v[156:159], v[80:95]
	v_add_f32_e32 v245, v118, v13
	v_add_f32_e32 v247, v119, v14
	v_add_f32_e32 v249, v120, v15
	v_cvt_pk_bf16_f32 v8, v12, v136
	v_cvt_pk_bf16_f32 v9, v13, v138
	v_cvt_pk_bf16_f32 v10, v14, v140
	v_cvt_pk_bf16_f32 v11, v15, v142
	v_cvt_pk_bf16_f32 v12, v112, v160
	v_cvt_pk_bf16_f32 v13, v114, v162
	v_cvt_pk_bf16_f32 v14, v128, v164
	v_cvt_pk_bf16_f32 v15, v115, v196
	v_cvt_pk_bf16_f32 v112, v117, v200
	v_cvt_pk_bf16_f32 v114, v119, v246
	v_cvt_pk_bf16_f32 v115, v120, v248
	v_add_f32_e32 v160, v160, v0
	v_add_f32_e32 v161, v161, v1
	v_add_u32_e32 v7, s30, v220
	v_add_f32_e32 v161, v160, v161
	v_add_f32_e32 v160, v160, v160
	v_mov_b32_e32 v133, v161
	v_add_f32_e32 v132, v162, v132
	v_add_f32_e32 v133, v163, v133
	s_waitcnt lgkmcnt(3)
	v_mfma_f32_32x32x16_bf16 v[64:79], v[232:235], v[2:5], v[64:79]
	v_add_f32_e32 v135, v132, v133
	v_add_f32_e32 v132, v164, v134
	v_add_f32_e32 v133, v165, v135
	ds_read_b128 v[116:119], v7
	ds_read_b128 v[120:123], v7 offset:4096
	ds_read_b128 v[124:127], v7 offset:8192
	ds_read_b128 v[128:131], v7 offset:12288
	v_add_f32_e32 v199, v132, v133
	v_add_f32_e32 v132, v196, v198
	v_add_f32_e32 v133, v197, v199
	s_waitcnt lgkmcnt(6)
	v_mfma_f32_32x32x16_bf16 v[48:63], v[236:239], v[2:5], v[48:63]
	v_add_f32_e32 v137, v132, v133
	v_add_f32_e32 v132, v200, v136
	v_add_f32_e32 v133, v201, v137
	s_nop 0
	v_add_f32_e32 v139, v132, v133
	v_add_f32_e32 v132, v244, v138
	v_add_f32_e32 v133, v245, v139
	s_waitcnt lgkmcnt(5)
	v_mfma_f32_32x32x16_bf16 v[32:47], v[224:227], v[2:5], v[32:47]
	v_add_f32_e32 v141, v132, v133
	v_add_f32_e32 v132, v246, v140
	v_add_f32_e32 v133, v247, v141
	s_nop 0
	v_add_f32_e32 v143, v132, v133
	v_add_f32_e32 v132, v248, v142
	v_add_f32_e32 v133, v249, v143
	s_waitcnt lgkmcnt(4)
	v_mfma_f32_32x32x16_bf16 v[16:31], v[240:243], v[2:5], v[16:31]
	v_add_f32_e32 v0, v132, v133
	v_add_f32_e32 v184, v6, v0
	s_waitcnt lgkmcnt(3)
	v_mfma_f32_32x32x16_bf16 v[64:79], v[116:119], v[8:11], v[64:79]
	v_add_u32_e32 v0, s30, v221
	s_waitcnt lgkmcnt(2)
	v_mfma_f32_32x32x16_bf16 v[48:63], v[120:123], v[8:11], v[48:63]
	s_waitcnt lgkmcnt(1)
	v_mfma_f32_32x32x16_bf16 v[32:47], v[124:127], v[8:11], v[32:47]
	ds_read_b128 v[2:5], v0
	ds_read_b128 v[116:119], v0 offset:4096
	ds_read_b128 v[120:123], v0 offset:8192
	ds_read_b128 v[124:127], v0 offset:12288
	s_waitcnt lgkmcnt(4)
	v_mfma_f32_32x32x16_bf16 v[16:31], v[128:131], v[8:11], v[16:31]
	v_add_u32_e32 v0, s30, v222
	ds_read_b128 v[6:9], v0
	ds_read_b128 v[128:131], v0 offset:4096
	s_waitcnt lgkmcnt(5)
	v_mfma_f32_32x32x16_bf16 v[64:79], v[2:5], v[12:15], v[64:79]
	ds_read_b128 v[2:5], v0 offset:8192
	ds_read_b128 v[132:135], v0 offset:12288
	v_max_f32_e32 v0, v97, v97
	v_max_f32_e32 v10, v81, v81
	v_max_f32_e32 v0, v0, v10
	v_max3_f32 v10, v96, v80, v98
	v_max3_f32 v0, v0, v99, v83
	v_max3_f32 v10, v10, v82, v100
	v_max3_f32 v0, v0, v101, v85
	s_waitcnt lgkmcnt(6)
	v_mfma_f32_32x32x16_bf16 v[48:63], v[116:119], v[12:15], v[48:63]
	v_max3_f32 v10, v10, v84, v102
	v_max3_f32 v0, v0, v103, v87
	v_max3_f32 v10, v10, v86, v104
	v_max3_f32 v0, v0, v105, v89
	v_max3_f32 v10, v10, v88, v106
	v_max3_f32 v0, v0, v107, v91
	v_max3_f32 v10, v10, v90, v108
	s_waitcnt lgkmcnt(5)
	v_mfma_f32_32x32x16_bf16 v[32:47], v[120:123], v[12:15], v[32:47]
	v_max3_f32 v0, v0, v109, v93
	v_max3_f32 v10, v10, v92, v110
	v_max3_f32 v0, v0, v111, v95
	v_max3_f32 v0, v10, v94, v0
	v_mov_b32_e32 v10, v0
	s_nop 1
	v_permlane32_swap_b32_e32 v0, v10
	s_waitcnt lgkmcnt(4)
	v_mfma_f32_32x32x16_bf16 v[16:31], v[124:127], v[12:15], v[16:31]
	s_waitcnt lgkmcnt(3)
	v_mfma_f32_32x32x16_bf16 v[64:79], v[6:9], v[112:115], v[64:79]
	v_max_f32_e32 v0, v0, v0
	s_waitcnt lgkmcnt(2)
	v_mfma_f32_32x32x16_bf16 v[48:63], v[128:131], v[112:115], v[48:63]
	s_waitcnt lgkmcnt(1)
	v_mfma_f32_32x32x16_bf16 v[32:47], v[2:5], v[112:115], v[32:47]
	v_max_f32_e32 v2, v10, v10
	v_max_f32_e32 v0, v0, v2
	v_cmp_lt_f32_e32 vcc, s93, v0
	s_waitcnt lgkmcnt(0)
	v_mfma_f32_32x32x16_bf16 v[16:31], v[132:135], v[112:115], v[16:31]
	s_cbranch_vccz .LBB0_597
	v_max_f32_e32 v0, v0, v0
	v_max_f32_e32 v2, 0, v0
	v_exp_f32_e64 v0, -v2
	v_add_f32_e32 v169, v169, v2
	v_sub_f32_e32 v111, v111, v2
	v_sub_f32_e32 v110, v110, v2
	v_pk_mul_f32 v[78:79], v[78:79], v[0:1] op_sel_hi:[1,0]
	v_pk_mul_f32 v[76:77], v[76:77], v[0:1] op_sel_hi:[1,0]
	v_pk_mul_f32 v[74:75], v[74:75], v[0:1] op_sel_hi:[1,0]
	v_pk_mul_f32 v[72:73], v[72:73], v[0:1] op_sel_hi:[1,0]
	v_pk_mul_f32 v[70:71], v[70:71], v[0:1] op_sel_hi:[1,0]
	v_pk_mul_f32 v[68:69], v[68:69], v[0:1] op_sel_hi:[1,0]
	v_pk_mul_f32 v[66:67], v[66:67], v[0:1] op_sel_hi:[1,0]
	v_pk_mul_f32 v[64:65], v[64:65], v[0:1] op_sel_hi:[1,0]
	v_pk_mul_f32 v[62:63], v[62:63], v[0:1] op_sel_hi:[1,0]
	v_pk_mul_f32 v[60:61], v[60:61], v[0:1] op_sel_hi:[1,0]
	v_pk_mul_f32 v[58:59], v[58:59], v[0:1] op_sel_hi:[1,0]
	v_pk_mul_f32 v[56:57], v[56:57], v[0:1] op_sel_hi:[1,0]
	v_pk_mul_f32 v[54:55], v[54:55], v[0:1] op_sel_hi:[1,0]
	v_pk_mul_f32 v[52:53], v[52:53], v[0:1] op_sel_hi:[1,0]
	v_pk_mul_f32 v[50:51], v[50:51], v[0:1] op_sel_hi:[1,0]
	v_pk_mul_f32 v[48:49], v[48:49], v[0:1] op_sel_hi:[1,0]
	v_pk_mul_f32 v[46:47], v[0:1], v[46:47] op_sel_hi:[0,1]
	v_pk_mul_f32 v[44:45], v[0:1], v[44:45] op_sel_hi:[0,1]
	v_pk_mul_f32 v[42:43], v[0:1], v[42:43] op_sel_hi:[0,1]
	v_pk_mul_f32 v[40:41], v[0:1], v[40:41] op_sel_hi:[0,1]
	v_pk_mul_f32 v[38:39], v[0:1], v[38:39] op_sel_hi:[0,1]
	v_pk_mul_f32 v[36:37], v[0:1], v[36:37] op_sel_hi:[0,1]
	v_pk_mul_f32 v[34:35], v[0:1], v[34:35] op_sel_hi:[0,1]
	v_pk_mul_f32 v[32:33], v[0:1], v[32:33] op_sel_hi:[0,1]
	v_pk_mul_f32 v[30:31], v[0:1], v[30:31] op_sel_hi:[0,1]
	v_pk_mul_f32 v[28:29], v[0:1], v[28:29] op_sel_hi:[0,1]
	v_pk_mul_f32 v[26:27], v[0:1], v[26:27] op_sel_hi:[0,1]
	v_pk_mul_f32 v[24:25], v[0:1], v[24:25] op_sel_hi:[0,1]
	v_pk_mul_f32 v[22:23], v[0:1], v[22:23] op_sel_hi:[0,1]
	v_pk_mul_f32 v[20:21], v[0:1], v[20:21] op_sel_hi:[0,1]
	v_pk_mul_f32 v[18:19], v[0:1], v[18:19] op_sel_hi:[0,1]
	v_pk_mul_f32 v[16:17], v[0:1], v[16:17] op_sel_hi:[0,1]
	v_sub_f32_e32 v109, v109, v2
	v_sub_f32_e32 v108, v108, v2
	v_sub_f32_e32 v107, v107, v2
	v_sub_f32_e32 v106, v106, v2
	v_sub_f32_e32 v105, v105, v2
	v_sub_f32_e32 v104, v104, v2
	v_sub_f32_e32 v103, v103, v2
	v_sub_f32_e32 v102, v102, v2
	v_sub_f32_e32 v101, v101, v2
	v_sub_f32_e32 v100, v100, v2
	v_sub_f32_e32 v99, v99, v2
	v_sub_f32_e32 v98, v98, v2
	v_sub_f32_e32 v97, v97, v2
	v_sub_f32_e32 v96, v96, v2
	v_sub_f32_e32 v95, v95, v2
	v_sub_f32_e32 v94, v94, v2
	v_sub_f32_e32 v93, v93, v2
	v_sub_f32_e32 v92, v92, v2
	v_sub_f32_e32 v91, v91, v2
	v_sub_f32_e32 v90, v90, v2
	v_sub_f32_e32 v89, v89, v2
	v_sub_f32_e32 v88, v88, v2
	v_sub_f32_e32 v87, v87, v2
	v_sub_f32_e32 v86, v86, v2
	v_sub_f32_e32 v85, v85, v2
	v_sub_f32_e32 v84, v84, v2
	v_sub_f32_e32 v83, v83, v2
	v_sub_f32_e32 v82, v82, v2
	v_sub_f32_e32 v81, v81, v2
	v_sub_f32_e32 v80, v80, v2
	v_mul_f32_e32 v184, v184, v0

.LBB0_606:
	s_or_b32 s42, s30, 1
	v_and_b32_e32 v12, 63, v219
	s_cmp_ge_u32 s42, s16
	s_cbranch_scc1 .LBB0_630
	s_cmp_gt_u32 s30, 27
	s_cselect_b64 s[12:13], -1, 0
	s_mov_b64 s[54:55], -1
	s_and_b64 vcc, exec, s[12:13]
	s_cbranch_vccz .LBB0_611
	s_cmp_lg_u32 s30, 28
	s_cbranch_scc1 .LBB0_610
	s_add_i32 s16, s37, 0x1c000
	s_mov_b32 m0, s16
	s_nop 0
	global_load_lds_dwordx4 v[174:175], off
	s_add_i32 s16, s37, 0x1c400
	s_mov_b32 m0, s16
	s_nop 0
	global_load_lds_dwordx4 v[176:177], off

.LBB0_611:
	s_andn2_b64 vcc, exec, s[54:55]
	s_cbranch_vccnz .LBB0_613
	s_lshl_b32 s16, s30, 14
	s_and_b32 s20, s16, 0x8000
	s_lshl_b32 s16, s30, 17
	v_lshl_add_u64 v[2:3], v[180:181], 0, s[16:17]
	s_mov_b64 s[54:55], 0x80000
	s_add_i32 s16, s20, s37
	v_lshl_add_u64 v[2:3], v[2:3], 0, s[54:55]
	s_mov_b32 m0, s16
	s_nop 0
	global_load_lds_dwordx4 v[2:3], off
	s_addk_i32 s16, 0x400
	v_lshl_add_u64 v[2:3], v[170:171], 1, v[2:3]
	s_mov_b32 m0, s16
	s_nop 0
	global_load_lds_dwordx4 v[2:3], off
	s_add_i32 s16, s30, 3
	s_lshl_b32 s20, s16, 14
	s_and_b32 s20, s20, 0xc000
	s_lshl_b32 s16, s16, 7
	v_lshl_add_u64 v[2:3], v[182:183], 0, s[16:17]
	s_add_i32 s16, s20, s3
	s_mov_b32 m0, s16
	s_nop 0
	global_load_lds_dwordx4 v[2:3], off
	v_lshl_add_u64 v[2:3], v[172:173], 1, v[2:3]
	s_addk_i32 s16, 0x400
	s_mov_b32 m0, s16
	s_nop 0
	global_load_lds_dwordx4 v[2:3], off
.LBB0_613:
	s_lshl_b32 s16, s42, 14
	s_and_b32 s16, s16, 0xc000
	s_add_i32 s16, s16, 0
	v_add_u32_e32 v0, s16, v210
	s_lshl_b32 s21, s42, 6
	ds_read_b128 v[2:5], v0
	ds_read_b128 v[6:9], v0 offset:8192
	v_cvt_f32_u32_e32 v0, s21
	v_fma_f32 v15, 2.0, v167, v185
	v_add_u32_e32 v10, s16, v211
	v_fma_f32 v113, 2.0, v185, v15
	v_sub_f32_e32 v0, v0, v205
	ds_read_b128 v[186:189], v10
	ds_read_b128 v[220:223], v10 offset:8192
	v_fma_f32 v11, v166, v0, -v169
	v_fmac_f32_e32 v113, 2.0, v15
	v_mov_b32_e32 v10, v166
	v_mov_b32_e32 v112, v167
	v_add_f32_e32 v112, v10, v112
	v_add_f32_e32 v113, v11, v113
	v_mov_b32_e32 v0, v11
	v_mov_b32_e32 v14, v113
	v_add_f32_e32 v118, v14, v112
	v_add_f32_e32 v119, v15, v113
	v_mov_b32_e32 v14, v112
	v_add_f32_e32 v120, v14, v0
	v_add_f32_e32 v121, v15, v0
	v_add_f32_e32 v136, v14, v119
	v_add_f32_e32 v137, v15, v119
	v_add_f32_e32 v126, v14, v121
	v_add_f32_e32 v127, v15, v121
	v_add_f32_e32 v114, v166, v0
	v_add_f32_e32 v115, v167, v0
	v_add_f32_e32 v162, v14, v127
	v_add_f32_e32 v163, v15, v127
	v_add_f32_e32 v14, v14, v137
	v_add_f32_e32 v15, v15, v137
	v_add_f32_e32 v116, v166, v113
	v_add_f32_e32 v117, v167, v113
	v_add_f32_e32 v122, v166, v121
	v_add_f32_e32 v123, v167, v121
	v_add_f32_e32 v124, v166, v119
	v_add_f32_e32 v125, v167, v119
	v_add_f32_e32 v138, v166, v137
	v_add_f32_e32 v139, v167, v137
	v_add_f32_e32 v142, v166, v15
	v_add_f32_e32 v143, v167, v15
	v_add_f32_e32 v196, v112, v15
	s_lshl_b32 s20, s30, 14
	v_add_f32_e32 v160, v166, v127
	v_add_f32_e32 v161, v167, v127
	v_add_f32_e32 v164, v166, v163
	v_add_f32_e32 v165, v167, v163
	v_add_f32_e32 v190, v112, v163
	v_mov_b32_e32 v128, v113
	v_mov_b32_e32 v129, v116
	v_mov_b32_e32 v130, v117
	v_mov_b32_e32 v131, v118
	v_mov_b32_e32 v132, v119
	v_mov_b32_e32 v133, v124
	v_mov_b32_e32 v134, v125
	v_mov_b32_e32 v135, v136
	v_mov_b32_e32 v136, v137
	v_mov_b32_e32 v137, v138
	v_mov_b32_e32 v138, v139
	v_mov_b32_e32 v139, v14
	v_mov_b32_e32 v140, v15
	v_mov_b32_e32 v141, v142
	v_mov_b32_e32 v142, v143
	v_mov_b32_e32 v143, v196
	v_mov_b32_e32 v112, v11
	v_mov_b32_e32 v113, v114
	v_mov_b32_e32 v114, v115
	v_mov_b32_e32 v115, v120
	v_mov_b32_e32 v116, v121
	v_mov_b32_e32 v117, v122
	v_mov_b32_e32 v118, v123
	v_mov_b32_e32 v119, v126
	v_mov_b32_e32 v120, v127
	v_mov_b32_e32 v121, v160
	v_mov_b32_e32 v122, v161
	v_mov_b32_e32 v123, v162
	v_mov_b32_e32 v124, v163
	v_mov_b32_e32 v125, v164
	v_mov_b32_e32 v126, v165
	v_mov_b32_e32 v127, v190
	s_waitcnt lgkmcnt(2)
	v_mfma_f32_32x32x16_bf16 v[128:143], v[6:9], v[144:147], v[128:143]
	v_add_u32_e32 v0, s16, v212
	v_exp_f32_e32 v13, v96
	v_exp_f32_e32 v96, v80
	v_exp_f32_e32 v161, v82
	v_exp_f32_e32 v10, v81
	v_exp_f32_e32 v160, v99
	v_exp_f32_e32 v14, v83
	v_mfma_f32_32x32x16_bf16 v[112:127], v[2:5], v[144:147], v[112:127]
	ds_read_b128 v[2:5], v0
	ds_read_b128 v[6:9], v0 offset:8192
	v_add_u32_e32 v0, s16, v213
	s_and_b32 s16, s20, 0x8000
	v_exp_f32_e32 v99, v84
	v_exp_f32_e32 v164, v101
	v_exp_f32_e32 v162, v85
	v_exp_f32_e32 v101, v88
	s_waitcnt lgkmcnt(3)
	v_mfma_f32_32x32x16_bf16 v[112:127], v[186:189], v[148:151], v[112:127]
	ds_read_b128 v[186:189], v0
	ds_read_b128 v[224:227], v0 offset:8192
	v_exp_f32_e32 v196, v105
	v_exp_f32_e32 v190, v89
	v_exp_f32_e32 v200, v107
	v_exp_f32_e32 v198, v91
	v_exp_f32_e32 v105, v92
	v_exp_f32_e32 v107, v94
	s_waitcnt lgkmcnt(4)
	v_mfma_f32_32x32x16_bf16 v[128:143], v[220:223], v[148:151], v[128:143]
	v_exp_f32_e32 v240, v93
	v_exp_f32_e32 v244, v95
	s_add_i32 s16, s16, 0
	v_add_u32_e32 v0, s16, v214
	ds_read_b128 v[220:223], v0
	ds_read_b128 v[228:231], v0 offset:4096
	ds_read_b128 v[232:235], v0 offset:8192
	ds_read_b128 v[236:239], v0 offset:12288
	v_exp_f32_e32 v98, v98
	v_exp_f32_e32 v0, v97
	s_waitcnt lgkmcnt(7)
	v_mfma_f32_32x32x16_bf16 v[112:127], v[2:5], v[152:155], v[112:127]
	v_exp_f32_e32 v4, v100
	v_exp_f32_e32 v100, v86
	v_exp_f32_e32 v5, v102
	v_exp_f32_e32 v97, v104
	v_exp_f32_e32 v102, v106
	v_exp_f32_e32 v104, v108
	v_exp_f32_e32 v106, v110
	s_waitcnt lgkmcnt(6)
	v_mfma_f32_32x32x16_bf16 v[128:143], v[6:9], v[152:155], v[128:143]
	v_exp_f32_e32 v242, v109
	v_exp_f32_e32 v246, v111
	v_add_f32_e32 v11, v96, v13
	v_add_f32_e32 v15, v161, v98
	v_add_f32_e32 v163, v99, v4
	v_add_f32_e32 v191, v101, v97
	v_add_f32_e32 v241, v105, v104
	s_waitcnt lgkmcnt(5)
	v_mfma_f32_32x32x16_bf16 v[112:127], v[186:189], v[156:159], v[112:127]
	v_exp_f32_e32 v188, v103
	v_exp_f32_e32 v186, v87
	v_exp_f32_e32 v103, v90
	v_mov_b64_e32 v[80:81], v[128:129]
	v_mov_b64_e32 v[82:83], v[130:131]
	v_mov_b64_e32 v[84:85], v[132:133]
	v_mov_b64_e32 v[86:87], v[134:135]
	v_mov_b64_e32 v[88:89], v[136:137]
	v_mov_b64_e32 v[90:91], v[138:139]
	v_mov_b64_e32 v[92:93], v[140:141]
	v_mov_b64_e32 v[94:95], v[142:143]
	v_add_f32_e32 v187, v100, v5
	v_add_f32_e32 v199, v103, v102
	s_waitcnt lgkmcnt(4)
	v_mfma_f32_32x32x16_bf16 v[80:95], v[224:227], v[156:159], v[80:95]
	v_add_f32_e32 v245, v107, v106
	v_cvt_pk_bf16_f32 v2, v13, v0
	v_cvt_pk_bf16_f32 v3, v98, v160
	v_cvt_pk_bf16_f32 v4, v4, v164
	v_cvt_pk_bf16_f32 v5, v5, v188
	v_cvt_pk_bf16_f32 v6, v97, v196
	v_cvt_pk_bf16_f32 v7, v102, v200
	v_cvt_pk_bf16_f32 v8, v104, v242
	v_cvt_pk_bf16_f32 v9, v106, v246
	v_cvt_pk_bf16_f32 v96, v96, v10
	v_cvt_pk_bf16_f32 v97, v161, v14
	v_cvt_pk_bf16_f32 v98, v99, v162
	v_cvt_pk_bf16_f32 v99, v100, v186
	v_cvt_pk_bf16_f32 v100, v101, v190
	v_cvt_pk_bf16_f32 v101, v103, v198
	v_cvt_pk_bf16_f32 v102, v105, v240
	v_cvt_pk_bf16_f32 v103, v107, v244
	v_add_f32_e32 v10, v10, v0
	v_add_f32_e32 v11, v11, v1
	v_xor_b32_e32 v13, 0x10020, v215
	v_add_f32_e32 v161, v10, v11
	v_add_f32_e32 v10, v14, v160
	v_add_f32_e32 v11, v15, v161
	v_add_u32_e32 v13, s16, v13
	v_add_f32_e32 v165, v10, v11
	v_add_f32_e32 v10, v162, v164
	v_add_f32_e32 v11, v163, v165
	s_waitcnt lgkmcnt(3)
	v_mfma_f32_32x32x16_bf16 v[64:79], v[220:223], v[2:5], v[64:79]
	v_add_f32_e32 v189, v10, v11
	v_add_f32_e32 v10, v186, v188
	v_add_f32_e32 v11, v187, v189
	ds_read_b128 v[104:107], v13
	ds_read_b128 v[108:111], v13 offset:4096
	ds_read_b128 v[128:131], v13 offset:8192
	ds_read_b128 v[132:135], v13 offset:12288
	v_add_f32_e32 v197, v10, v11
	v_add_f32_e32 v10, v190, v196
	v_add_f32_e32 v11, v191, v197
	s_waitcnt lgkmcnt(6)
	v_mfma_f32_32x32x16_bf16 v[48:63], v[228:231], v[2:5], v[48:63]
	v_add_f32_e32 v201, v10, v11
	v_add_f32_e32 v10, v198, v200
	v_add_f32_e32 v11, v199, v201
	s_nop 0
	v_add_f32_e32 v243, v10, v11
	v_add_f32_e32 v10, v240, v242
	v_add_f32_e32 v11, v241, v243
	s_waitcnt lgkmcnt(5)
	v_mfma_f32_32x32x16_bf16 v[32:47], v[232:235], v[2:5], v[32:47]
	v_add_f32_e32 v247, v10, v11
	v_add_f32_e32 v10, v244, v246
	v_add_f32_e32 v11, v245, v247
	s_nop 0
	v_add_f32_e32 v0, v10, v11
	v_add_f32_e32 v184, v184, v0
	s_waitcnt lgkmcnt(4)
	v_mfma_f32_32x32x16_bf16 v[16:31], v[236:239], v[2:5], v[16:31]
	v_xor_b32_e32 v0, 0x10040, v215
	s_waitcnt lgkmcnt(3)
	v_mfma_f32_32x32x16_bf16 v[64:79], v[104:107], v[6:9], v[64:79]
	v_add_u32_e32 v0, s16, v0
	s_waitcnt lgkmcnt(2)
	v_mfma_f32_32x32x16_bf16 v[48:63], v[108:111], v[6:9], v[48:63]
	s_waitcnt lgkmcnt(1)
	v_mfma_f32_32x32x16_bf16 v[32:47], v[128:131], v[6:9], v[32:47]
	ds_read_b128 v[2:5], v0
	ds_read_b128 v[104:107], v0 offset:4096
	ds_read_b128 v[108:111], v0 offset:8192
	ds_read_b128 v[128:131], v0 offset:12288
	s_waitcnt lgkmcnt(4)
	v_mfma_f32_32x32x16_bf16 v[16:31], v[132:135], v[6:9], v[16:31]
	v_xor_b32_e32 v0, 0x10060, v215
	v_add_u32_e32 v0, s16, v0
	ds_read_b128 v[6:9], v0
	ds_read_b128 v[132:135], v0 offset:4096
	s_waitcnt lgkmcnt(5)
	v_mfma_f32_32x32x16_bf16 v[64:79], v[2:5], v[96:99], v[64:79]
	ds_read_b128 v[2:5], v0 offset:8192
	ds_read_b128 v[136:139], v0 offset:12288
	v_max_f32_e32 v0, v81, v81
	v_max_f32_e32 v10, v113, v113
	v_max_f32_e32 v0, v10, v0
	v_max3_f32 v10, v112, v80, v114
	v_max3_f32 v0, v0, v115, v83
	v_max3_f32 v10, v10, v82, v116
	v_max3_f32 v0, v0, v117, v85
	s_waitcnt lgkmcnt(6)
	v_mfma_f32_32x32x16_bf16 v[48:63], v[104:107], v[96:99], v[48:63]
	v_max3_f32 v10, v10, v84, v118
	v_max3_f32 v0, v0, v119, v87
	v_max3_f32 v10, v10, v86, v120
	v_max3_f32 v0, v0, v121, v89
	v_max3_f32 v10, v10, v88, v122
	v_max3_f32 v0, v0, v123, v91
	v_max3_f32 v10, v10, v90, v124
	s_waitcnt lgkmcnt(5)
	v_mfma_f32_32x32x16_bf16 v[32:47], v[108:111], v[96:99], v[32:47]
	v_max3_f32 v0, v0, v125, v93
	v_max3_f32 v10, v10, v92, v126
	v_max3_f32 v0, v0, v127, v95
	v_max3_f32 v0, v10, v94, v0
	v_mov_b32_e32 v10, v0
	s_nop 1
	v_permlane32_swap_b32_e32 v0, v10
	s_waitcnt lgkmcnt(4)
	v_mfma_f32_32x32x16_bf16 v[16:31], v[128:131], v[96:99], v[16:31]
	s_waitcnt lgkmcnt(3)
	v_mfma_f32_32x32x16_bf16 v[64:79], v[6:9], v[100:103], v[64:79]
	v_max_f32_e32 v0, v0, v0
	s_waitcnt lgkmcnt(2)
	v_mfma_f32_32x32x16_bf16 v[48:63], v[132:135], v[100:103], v[48:63]
	s_waitcnt lgkmcnt(1)
	v_mfma_f32_32x32x16_bf16 v[32:47], v[2:5], v[100:103], v[32:47]
	v_max_f32_e32 v2, v10, v10
	v_max_f32_e32 v0, v0, v2
	v_cmp_lt_f32_e32 vcc, s93, v0
	s_waitcnt lgkmcnt(0)
	v_mfma_f32_32x32x16_bf16 v[16:31], v[136:139], v[100:103], v[16:31]
	s_cbranch_vccz .LBB0_671
	v_max_f32_e32 v0, v0, v0
	v_max_f32_e32 v2, 0, v0
	v_exp_f32_e64 v0, -v2
	v_add_f32_e32 v169, v169, v2
	v_sub_f32_e32 v111, v127, v2
	v_sub_f32_e32 v110, v126, v2
	v_pk_mul_f32 v[78:79], v[78:79], v[0:1] op_sel_hi:[1,0]
	v_pk_mul_f32 v[76:77], v[76:77], v[0:1] op_sel_hi:[1,0]
	v_pk_mul_f32 v[74:75], v[74:75], v[0:1] op_sel_hi:[1,0]
	v_pk_mul_f32 v[72:73], v[72:73], v[0:1] op_sel_hi:[1,0]
	v_pk_mul_f32 v[70:71], v[70:71], v[0:1] op_sel_hi:[1,0]
	v_pk_mul_f32 v[68:69], v[68:69], v[0:1] op_sel_hi:[1,0]
	v_pk_mul_f32 v[66:67], v[66:67], v[0:1] op_sel_hi:[1,0]
	v_pk_mul_f32 v[64:65], v[64:65], v[0:1] op_sel_hi:[1,0]
	v_pk_mul_f32 v[62:63], v[62:63], v[0:1] op_sel_hi:[1,0]
	v_pk_mul_f32 v[60:61], v[60:61], v[0:1] op_sel_hi:[1,0]
	v_pk_mul_f32 v[58:59], v[58:59], v[0:1] op_sel_hi:[1,0]
	v_pk_mul_f32 v[56:57], v[56:57], v[0:1] op_sel_hi:[1,0]
	v_pk_mul_f32 v[54:55], v[54:55], v[0:1] op_sel_hi:[1,0]
	v_pk_mul_f32 v[52:53], v[52:53], v[0:1] op_sel_hi:[1,0]
	v_pk_mul_f32 v[50:51], v[50:51], v[0:1] op_sel_hi:[1,0]
	v_pk_mul_f32 v[48:49], v[48:49], v[0:1] op_sel_hi:[1,0]
	v_pk_mul_f32 v[46:47], v[0:1], v[46:47] op_sel_hi:[0,1]
	v_pk_mul_f32 v[44:45], v[0:1], v[44:45] op_sel_hi:[0,1]
	v_pk_mul_f32 v[42:43], v[0:1], v[42:43] op_sel_hi:[0,1]
	v_pk_mul_f32 v[40:41], v[0:1], v[40:41] op_sel_hi:[0,1]
	v_pk_mul_f32 v[38:39], v[0:1], v[38:39] op_sel_hi:[0,1]
	v_pk_mul_f32 v[36:37], v[0:1], v[36:37] op_sel_hi:[0,1]
	v_pk_mul_f32 v[34:35], v[0:1], v[34:35] op_sel_hi:[0,1]
	v_pk_mul_f32 v[32:33], v[0:1], v[32:33] op_sel_hi:[0,1]
	v_pk_mul_f32 v[30:31], v[0:1], v[30:31] op_sel_hi:[0,1]
	v_pk_mul_f32 v[28:29], v[0:1], v[28:29] op_sel_hi:[0,1]
	v_pk_mul_f32 v[26:27], v[0:1], v[26:27] op_sel_hi:[0,1]
	v_pk_mul_f32 v[24:25], v[0:1], v[24:25] op_sel_hi:[0,1]
	v_pk_mul_f32 v[22:23], v[0:1], v[22:23] op_sel_hi:[0,1]
	v_pk_mul_f32 v[20:21], v[0:1], v[20:21] op_sel_hi:[0,1]
	v_pk_mul_f32 v[18:19], v[0:1], v[18:19] op_sel_hi:[0,1]
	v_pk_mul_f32 v[16:17], v[0:1], v[16:17] op_sel_hi:[0,1]
	v_sub_f32_e32 v109, v125, v2
	v_sub_f32_e32 v108, v124, v2
	v_sub_f32_e32 v107, v123, v2
	v_sub_f32_e32 v106, v122, v2
	v_sub_f32_e32 v105, v121, v2
	v_sub_f32_e32 v104, v120, v2
	v_sub_f32_e32 v103, v119, v2
	v_sub_f32_e32 v102, v118, v2
	v_sub_f32_e32 v101, v117, v2
	v_sub_f32_e32 v100, v116, v2
	v_sub_f32_e32 v99, v115, v2
	v_sub_f32_e32 v98, v114, v2
	v_sub_f32_e32 v97, v113, v2
	v_sub_f32_e32 v96, v112, v2
	v_sub_f32_e32 v95, v95, v2
	v_sub_f32_e32 v94, v94, v2
	v_sub_f32_e32 v93, v93, v2
	v_sub_f32_e32 v92, v92, v2
	v_sub_f32_e32 v91, v91, v2
	v_sub_f32_e32 v90, v90, v2
	v_sub_f32_e32 v89, v89, v2
	v_sub_f32_e32 v88, v88, v2
	v_sub_f32_e32 v87, v87, v2
	v_sub_f32_e32 v86, v86, v2
	v_sub_f32_e32 v85, v85, v2
	v_sub_f32_e32 v84, v84, v2
	v_sub_f32_e32 v83, v83, v2
	v_sub_f32_e32 v82, v82, v2
	v_sub_f32_e32 v81, v81, v2
	v_sub_f32_e32 v80, v80, v2
	v_mul_f32_e32 v184, v184, v0
	s_mov_b64 s[54:55], -1
	s_and_b64 vcc, exec, s[12:13]
	s_cbranch_vccz .LBB0_616

.LBB0_618:
	s_cmp_gt_i32 s42, 27
	s_cselect_b64 s[12:13], -1, 0
	s_mov_b64 s[40:41], -1
	s_and_b64 vcc, exec, s[12:13]
	s_cbranch_vccz .LBB0_622
	s_cmp_lg_u32 s42, 28
	s_cbranch_scc1 .LBB0_621
	s_add_i32 s16, s37, 0x1c000
	s_mov_b32 m0, s16
	s_nop 0
	global_load_lds_dwordx4 v[174:175], off
	s_add_i32 s16, s37, 0x1c400
	s_mov_b32 m0, s16
	s_nop 0
	global_load_lds_dwordx4 v[176:177], off

; #define AT_ISSUE_K(tt) do { const unsigned so_ = (unsigned)(((tt) & 3) * AT_SLOT); const bf16_t* kp_ = kgp + (size_t)(tt) * 64 * DM; \
;         glds16(kp_, (unsigned)__builtin_amdgcn_readfirstlane(kdst + so_)); glds16(kp_ + kx1, (unsigned)__builtin_amdgcn_readfirstlane(kdst + so_ + 1024)); } while (0)
; #define AT_ISSUE_V(tt) do { const unsigned so_ = (unsigned)(((tt) & 3) * AT_SLOT); const bf16_t* vp_ = vgp + (tt) * 64; \
;         glds16(vp_, (unsigned)__builtin_amdgcn_readfirstlane(vdst + so_)); glds16(vp_ + vx1, (unsigned)__builtin_amdgcn_readfirstlane(vdst + so_ + 1024)); } while (0)
; #define AT_BAR(N) asm volatile("s_waitcnt vmcnt(" #N ") lgkmcnt(0)\n\ts_barrier" ::: "memory")
; template <bool STORE> __device__ __forceinline__ void attn_unit(LAS unsigned char* lds, bf16_t* Q, const bf16_t* Kg, const bf16_t* VT, const float* subg, float lam, float outscale, int unit, const int wave_s) {
;     ...
;     AT_ISSUE_K(0); AT_ISSUE_V(0); AT_ISSUE_K(1); AT_ISSUE_V(1); AT_ISSUE_K(2); AT_ISSUE_V(2); AT_ISSUE_K(3);
;     AT_BAR(8);
;     f32x16 o[4]; o[0] = f32x16{}; o[1] = f32x16{}; o[2] = f32x16{}; o[3] = f32x16{};
;     float mref = sself + 6.0f, lsum = 0.f;
;     const int koff = q * 256 + (((map * 8 + hi) ^ (q & 15)) << 4), voff = AT_VOFF + q * 128 + ((hi ^ ((q >> 1) & 7)) << 4);
;     const float qposf = (float)(qrow0 + q - 4 * hi);
;     f32x16 x0, x1, n0, n1;
.LBB0_622:
	s_andn2_b64 vcc, exec, s[40:41]
	s_cbranch_vccnz .LBB0_624
	s_lshl_b32 s16, s42, 14
	s_ashr_i32 s43, s42, 31
	s_and_b32 s16, s16, 0xc000
	s_lshl_b64 s[20:21], s[42:43], 17
	v_lshl_add_u64 v[2:3], v[180:181], 0, s[20:21]
	s_mov_b64 s[20:21], 0x80000
	s_add_i32 s16, s16, s37
	v_lshl_add_u64 v[2:3], v[2:3], 0, s[20:21]
	s_mov_b32 m0, s16
	s_nop 0
	global_load_lds_dwordx4 v[2:3], off
	s_addk_i32 s16, 0x400
	v_lshl_add_u64 v[2:3], v[170:171], 1, v[2:3]
	s_mov_b32 m0, s16
	s_nop 0
	global_load_lds_dwordx4 v[2:3], off
	s_add_i32 s16, s42, 3
	s_lshl_b32 s20, s16, 14
	s_and_b32 s28, s20, 0xc000
	s_lshl_b32 s20, s16, 6
	s_ashr_i32 s21, s20, 31
	v_lshl_add_u64 v[2:3], s[20:21], 1, v[182:183]
	s_add_i32 s16, s28, s3
	s_mov_b32 m0, s16
	s_nop 0
	global_load_lds_dwordx4 v[2:3], off
	v_lshl_add_u64 v[2:3], v[172:173], 1, v[2:3]
	s_addk_i32 s16, 0x400
	s_mov_b32 m0, s16
	s_nop 0
	global_load_lds_dwordx4 v[2:3], off
.LBB0_624:
	s_add_i32 s16, s42, 1
	s_lshl_b32 s20, s16, 14
	s_lshl_b32 s28, s16, 6
	s_and_b32 s20, s20, 0xc000
	v_cvt_f32_i32_e32 v13, s28
	s_add_i32 s20, s20, 0
	v_add_u32_e32 v0, s20, v210
	ds_read_b128 v[2:5], v0
	ds_read_b128 v[6:9], v0 offset:8192
	v_add_u32_e32 v0, s20, v211
	ds_read_b128 v[180:183], v0
	ds_read_b128 v[186:189], v0 offset:8192
	v_sub_f32_e32 v0, v13, v205
	v_mul_f32_e32 v10, 0, v166
	v_mul_f32_e32 v11, v10, v0
	v_mov_b32_e32 v168, v10
	v_add_f32_e32 v14, v10, v168
	v_sub_f32_e32 v128, v10, v168
	v_sub_f32_e32 v129, v11, v169
	s_lshl_b32 s21, s42, 14
	v_mov_b32_e32 v15, v129
	v_add_f32_e32 v112, v14, v14
	v_add_f32_e32 v113, v15, v15
	s_nop 0
	v_pk_fma_f32 v[114:115], v[14:15], 2.0, v[112:113] op_sel_hi:[1,0,1]
	s_nop 0
	v_pk_fma_f32 v[112:113], v[112:113], 2.0, v[114:115] op_sel_hi:[1,0,1]
	v_mov_b32_e32 v121, v114
	v_pk_fma_f32 v[112:113], v[114:115], 2.0, v[112:113] op_sel_hi:[1,0,1]
	s_nop 0
	v_mov_b32_e32 v11, v112
	v_add_f32_e32 v112, v10, v14
	v_add_f32_e32 v113, v11, v15
	v_mov_b32_e32 v11, v14
	v_pk_mov_b32 v[118:119], v[112:113], v[114:115] op_sel:[1,0]
	v_mov_b32_e32 v120, v112
	v_add_f32_e32 v118, v118, v112
	v_add_f32_e32 v119, v119, v113
	v_add_f32_e32 v132, v120, v129
	v_add_f32_e32 v133, v121, v129
	v_add_f32_e32 v124, v120, v119
	v_add_f32_e32 v125, v121, v119
	v_add_f32_e32 v136, v120, v133
	v_add_f32_e32 v137, v121, v133
	v_add_f32_e32 v130, v120, v125
	v_add_f32_e32 v131, v121, v125
	v_add_f32_e32 v140, v120, v137
	v_add_f32_e32 v141, v121, v137
	v_add_f32_e32 v14, v10, v129
	v_add_f32_e32 v15, v11, v129
	v_add_f32_e32 v116, v10, v113
	v_add_f32_e32 v117, v11, v113
	v_add_f32_e32 v134, v10, v133
	v_add_f32_e32 v135, v11, v133
	v_add_f32_e32 v122, v10, v119
	v_add_f32_e32 v123, v11, v119
	v_add_f32_e32 v138, v10, v137
	v_add_f32_e32 v139, v11, v137
	v_add_f32_e32 v126, v10, v125
	v_add_f32_e32 v127, v11, v125
	v_add_f32_e32 v142, v10, v141
	v_add_f32_e32 v143, v11, v141
	v_add_f32_e32 v10, v10, v131
	v_add_f32_e32 v11, v11, v131
	v_add_f32_e32 v162, v112, v131
	v_add_f32_e32 v160, v112, v141
	v_mov_b32_e32 v112, v113
	v_mov_b32_e32 v113, v116
	v_mov_b32_e32 v114, v117
	v_mov_b32_e32 v115, v118
	v_mov_b32_e32 v116, v119
	v_mov_b32_e32 v117, v122
	v_mov_b32_e32 v118, v123
	v_mov_b32_e32 v119, v124
	v_mov_b32_e32 v120, v125
	v_mov_b32_e32 v121, v126
	v_mov_b32_e32 v122, v127
	v_mov_b32_e32 v123, v130
	v_mov_b32_e32 v124, v131
	v_mov_b32_e32 v125, v10
	v_mov_b32_e32 v126, v11
	v_mov_b32_e32 v127, v162
	v_mov_b32_e32 v128, v129
	v_mov_b32_e32 v129, v14
	v_mov_b32_e32 v130, v15
	v_mov_b32_e32 v131, v132
	v_mov_b32_e32 v132, v133
	v_mov_b32_e32 v133, v134
	v_mov_b32_e32 v134, v135
	v_mov_b32_e32 v135, v136
	v_mov_b32_e32 v136, v137
	v_mov_b32_e32 v137, v138
	v_mov_b32_e32 v138, v139
	v_mov_b32_e32 v139, v140
	v_mov_b32_e32 v140, v141
	v_mov_b32_e32 v141, v142
	v_mov_b32_e32 v142, v143
	v_mov_b32_e32 v143, v160
	s_waitcnt lgkmcnt(2)
	v_mfma_f32_32x32x16_bf16 v[112:127], v[6:9], v[144:147], v[112:127]
	v_add_u32_e32 v0, s20, v212
	v_exp_f32_e32 v161, v80
	v_exp_f32_e32 v80, v98
	v_exp_f32_e32 v98, v82
	v_exp_f32_e32 v10, v81
	v_exp_f32_e32 v160, v99
	v_exp_f32_e32 v14, v83
	v_mfma_f32_32x32x16_bf16 v[128:143], v[2:5], v[144:147], v[128:143]
	ds_read_b128 v[2:5], v0
	ds_read_b128 v[6:9], v0 offset:8192
	v_add_u32_e32 v0, s20, v213
	s_and_b32 s20, s21, 0xc000
	s_add_i32 s20, s20, 0
	v_exp_f32_e32 v162, v85
	v_exp_f32_e32 v81, v104
	v_exp_f32_e32 v88, v88
	s_waitcnt lgkmcnt(3)
	v_mfma_f32_32x32x16_bf16 v[128:143], v[180:183], v[148:151], v[128:143]
	ds_read_b128 v[180:183], v0
	ds_read_b128 v[220:223], v0 offset:8192
	v_add_u32_e32 v0, s20, v214
	v_exp_f32_e32 v82, v106
	v_exp_f32_e32 v90, v90
	v_exp_f32_e32 v104, v105
	v_exp_f32_e32 v190, v89
	v_exp_f32_e32 v106, v107
	s_waitcnt lgkmcnt(4)
	v_mfma_f32_32x32x16_bf16 v[112:127], v[186:189], v[148:151], v[112:127]
	ds_read_b128 v[186:189], v0
	ds_read_b128 v[224:227], v0 offset:4096
	ds_read_b128 v[228:231], v0 offset:8192
	ds_read_b128 v[232:235], v0 offset:12288
	v_exp_f32_e32 v196, v91
	v_exp_f32_e32 v83, v108
	v_exp_f32_e32 v89, v92
	v_exp_f32_e32 v91, v94
	v_exp_f32_e32 v108, v109
	v_exp_f32_e32 v96, v96
	s_waitcnt lgkmcnt(7)
	v_mfma_f32_32x32x16_bf16 v[128:143], v[2:5], v[152:155], v[128:143]
	v_exp_f32_e32 v3, v84
	v_exp_f32_e32 v5, v86
	v_exp_f32_e32 v84, v110
	v_exp_f32_e32 v110, v111
	v_exp_f32_e32 v0, v97
	v_exp_f32_e32 v2, v100
	v_exp_f32_e32 v4, v102
	s_waitcnt lgkmcnt(6)
	v_mfma_f32_32x32x16_bf16 v[112:127], v[6:9], v[152:155], v[112:127]
	v_exp_f32_e32 v164, v101
	v_exp_f32_e32 v198, v93
	v_exp_f32_e32 v200, v95
	v_add_f32_e32 v15, v98, v80
	v_add_f32_e32 v191, v88, v81
	v_add_f32_e32 v197, v90, v82
	v_add_f32_e32 v199, v89, v83
	s_waitcnt lgkmcnt(5)
	v_mfma_f32_32x32x16_bf16 v[128:143], v[180:183], v[156:159], v[128:143]
	v_exp_f32_e32 v180, v87
	v_exp_f32_e32 v182, v103
	v_add_f32_e32 v201, v91, v84
	v_cvt_pk_bf16_f32 v7, v80, v160
	v_cvt_pk_bf16_f32 v80, v81, v104
	v_cvt_pk_bf16_f32 v81, v82, v106
	v_cvt_pk_bf16_f32 v82, v83, v108
	v_cvt_pk_bf16_f32 v83, v84, v110
	v_cvt_pk_bf16_f32 v84, v161, v10
	v_cvt_pk_bf16_f32 v85, v98, v14
	v_cvt_pk_bf16_f32 v86, v3, v162
	v_cvt_pk_bf16_f32 v87, v5, v180
	v_add_f32_e32 v11, v161, v96
	v_add_f32_e32 v163, v3, v2
	v_add_f32_e32 v181, v5, v4
	s_waitcnt lgkmcnt(4)
	v_mfma_f32_32x32x16_bf16 v[112:127], v[220:223], v[156:159], v[112:127]
	v_cvt_pk_bf16_f32 v6, v96, v0
	v_cvt_pk_bf16_f32 v8, v2, v164
	v_cvt_pk_bf16_f32 v9, v4, v182
	v_cvt_pk_bf16_f32 v2, v88, v190
	v_cvt_pk_bf16_f32 v3, v90, v196
	v_cvt_pk_bf16_f32 v4, v89, v198
	v_cvt_pk_bf16_f32 v5, v91, v200
	v_add_f32_e32 v10, v10, v0
	v_add_f32_e32 v11, v11, v1
	v_xor_b32_e32 v88, 0x10020, v215
	v_add_f32_e32 v161, v10, v11
	v_add_f32_e32 v10, v14, v160
	v_add_f32_e32 v11, v15, v161
	v_add_u32_e32 v100, s20, v88
	v_add_f32_e32 v165, v10, v11
	v_add_f32_e32 v10, v162, v164
	v_add_f32_e32 v11, v163, v165
	s_waitcnt lgkmcnt(3)
	v_mfma_f32_32x32x16_bf16 v[64:79], v[186:189], v[6:9], v[64:79]
	v_add_f32_e32 v183, v10, v11
	v_add_f32_e32 v10, v180, v182
	v_add_f32_e32 v11, v181, v183
	ds_read_b128 v[88:91], v100
	ds_read_b128 v[92:95], v100 offset:4096
	ds_read_b128 v[96:99], v100 offset:8192
	ds_read_b128 v[100:103], v100 offset:12288
	v_add_f32_e32 v105, v10, v11
	v_add_f32_e32 v10, v190, v104
	v_add_f32_e32 v11, v191, v105
	s_waitcnt lgkmcnt(6)
	v_mfma_f32_32x32x16_bf16 v[48:63], v[224:227], v[6:9], v[48:63]
	v_add_f32_e32 v107, v10, v11
	v_add_f32_e32 v10, v196, v106
	v_add_f32_e32 v11, v197, v107
	s_nop 0
	v_add_f32_e32 v109, v10, v11
	v_add_f32_e32 v10, v198, v108
	v_add_f32_e32 v11, v199, v109
	s_waitcnt lgkmcnt(5)
	v_mfma_f32_32x32x16_bf16 v[32:47], v[228:231], v[6:9], v[32:47]
	v_add_f32_e32 v111, v10, v11
	v_add_f32_e32 v10, v200, v110
	v_add_f32_e32 v11, v201, v111
	s_nop 0
	v_add_f32_e32 v0, v10, v11
	v_add_f32_e32 v184, v184, v0
	s_waitcnt lgkmcnt(4)
	v_mfma_f32_32x32x16_bf16 v[16:31], v[232:235], v[6:9], v[16:31]
	v_xor_b32_e32 v0, 0x10040, v215
	s_waitcnt lgkmcnt(3)
	v_mfma_f32_32x32x16_bf16 v[64:79], v[88:91], v[80:83], v[64:79]
	v_add_u32_e32 v0, s20, v0
	s_waitcnt lgkmcnt(2)
	v_mfma_f32_32x32x16_bf16 v[48:63], v[92:95], v[80:83], v[48:63]
	s_waitcnt lgkmcnt(1)
	v_mfma_f32_32x32x16_bf16 v[32:47], v[96:99], v[80:83], v[32:47]
	ds_read_b128 v[6:9], v0
	ds_read_b128 v[88:91], v0 offset:4096
	ds_read_b128 v[92:95], v0 offset:8192
	ds_read_b128 v[96:99], v0 offset:12288
	s_waitcnt lgkmcnt(4)
	v_mfma_f32_32x32x16_bf16 v[16:31], v[100:103], v[80:83], v[16:31]
	v_xor_b32_e32 v0, 0x10060, v215
	v_add_u32_e32 v0, s20, v0
	ds_read_b128 v[180:183], v0
	ds_read_b128 v[186:189], v0 offset:4096
	ds_read_b128 v[220:223], v0 offset:8192
	ds_read_b128 v[224:227], v0 offset:12288
	v_sub_f32_e32 v0, v205, v13
	s_waitcnt lgkmcnt(7)
	v_mfma_f32_32x32x16_bf16 v[64:79], v[6:9], v[84:87], v[64:79]
	v_add_f32_e32 v7, -1.0, v0
	v_and_b32_e32 v6, 0x7fffffff, v0
	v_and_b32_e32 v7, 0x7fffffff, v7
	s_mov_b32 s20, -2.0
	s_mov_b32 s21, 0xc0400000
	s_waitcnt lgkmcnt(4)
	v_mfma_f32_32x32x16_bf16 v[16:31], v[96:99], v[84:87], v[16:31]
	v_fma_f32 v96, -v166, v6, v128
	v_fma_f32 v97, -v166, v7, v129
	v_add_f32_e32 v6, 0xc2000000, v0
	v_add_f32_e32 v7, -1.0, v6
	v_and_b32_e32 v8, 0x7fffffff, v6
	v_and_b32_e32 v9, 0x7fffffff, v7
	v_pk_fma_f32 v[80:81], v[166:167], v[8:9], v[112:113] op_sel_hi:[0,1,1] neg_lo:[1,0,0] neg_hi:[1,0,0]
	v_add_f32_e32 v8, s20, v0
	v_add_f32_e32 v9, s21, v0
	v_and_b32_e32 v9, 0x7fffffff, v9
	v_and_b32_e32 v8, 0x7fffffff, v8
	v_pk_fma_f32 v[98:99], v[166:167], v[8:9], v[130:131] op_sel_hi:[0,1,1] neg_lo:[1,0,0] neg_hi:[1,0,0]
	v_add_f32_e32 v8, s20, v6
	v_add_f32_e32 v9, s21, v6
	s_mov_b32 s20, 0xc1000000
	v_and_b32_e32 v9, 0x7fffffff, v9
	v_and_b32_e32 v8, 0x7fffffff, v8
	s_mov_b32 s21, 0xc1100000
	v_pk_fma_f32 v[82:83], v[166:167], v[8:9], v[114:115] op_sel_hi:[0,1,1] neg_lo:[1,0,0] neg_hi:[1,0,0]
	v_add_f32_e32 v8, s20, v0
	v_add_f32_e32 v9, s21, v0
	v_and_b32_e32 v9, 0x7fffffff, v9
	v_and_b32_e32 v8, 0x7fffffff, v8
	v_pk_fma_f32 v[100:101], v[166:167], v[8:9], v[132:133] op_sel_hi:[0,1,1] neg_lo:[1,0,0] neg_hi:[1,0,0]
	v_add_f32_e32 v8, s20, v6
	v_add_f32_e32 v9, s21, v6
	s_mov_b32 s20, 0xc1200000
	v_and_b32_e32 v9, 0x7fffffff, v9
	v_and_b32_e32 v8, 0x7fffffff, v8
	s_mov_b32 s21, 0xc1300000
	v_mfma_f32_32x32x16_bf16 v[48:63], v[88:91], v[84:87], v[48:63]
	v_mfma_f32_32x32x16_bf16 v[32:47], v[92:95], v[84:87], v[32:47]
	v_fma_f32 v84, -v166, v8, v116
	v_fma_f32 v85, -v166, v9, v117
	v_add_f32_e64 v8, v0, s20
	v_add_f32_e64 v9, v0, s21
	v_and_b32_e32 v9, 0x7fffffff, v9
	v_and_b32_e32 v8, 0x7fffffff, v8
	v_pk_fma_f32 v[102:103], v[166:167], v[8:9], v[134:135] op_sel_hi:[0,1,1] neg_lo:[1,0,0] neg_hi:[1,0,0]
	v_add_f32_e32 v8, s20, v6
	v_add_f32_e32 v9, s21, v6
	s_mov_b32 s20, 0xc1800000
	v_and_b32_e32 v9, 0x7fffffff, v9
	v_and_b32_e32 v8, 0x7fffffff, v8
	s_mov_b32 s21, 0xc1880000
	v_pk_fma_f32 v[86:87], v[166:167], v[8:9], v[118:119] op_sel_hi:[0,1,1] neg_lo:[1,0,0] neg_hi:[1,0,0]
	v_add_f32_e32 v8, s20, v0
	v_add_f32_e32 v9, s21, v0
	v_and_b32_e32 v9, 0x7fffffff, v9
	v_and_b32_e32 v8, 0x7fffffff, v8
	v_pk_fma_f32 v[104:105], v[166:167], v[8:9], v[136:137] op_sel_hi:[0,1,1] neg_lo:[1,0,0] neg_hi:[1,0,0]
	v_add_f32_e32 v8, s20, v6
	v_add_f32_e32 v9, s21, v6
	s_mov_b32 s20, 0xc1900000
	v_and_b32_e32 v9, 0x7fffffff, v9
	v_and_b32_e32 v8, 0x7fffffff, v8
	s_mov_b32 s21, 0xc1980000
	v_pk_fma_f32 v[88:89], v[166:167], v[8:9], v[120:121] op_sel_hi:[0,1,1] neg_lo:[1,0,0] neg_hi:[1,0,0]
	v_add_f32_e32 v8, s20, v0
	v_add_f32_e32 v9, s21, v0
	v_and_b32_e32 v9, 0x7fffffff, v9
	v_and_b32_e32 v8, 0x7fffffff, v8
	v_pk_fma_f32 v[106:107], v[166:167], v[8:9], v[138:139] op_sel_hi:[0,1,1] neg_lo:[1,0,0] neg_hi:[1,0,0]
	v_add_f32_e32 v8, s20, v6
	v_add_f32_e32 v9, s21, v6
	s_mov_b32 s20, 0xc1c00000
	v_and_b32_e32 v9, 0x7fffffff, v9
	v_and_b32_e32 v8, 0x7fffffff, v8
	s_mov_b32 s21, 0xc1c80000
	v_pk_fma_f32 v[90:91], v[166:167], v[8:9], v[122:123] op_sel_hi:[0,1,1] neg_lo:[1,0,0] neg_hi:[1,0,0]
	v_add_f32_e32 v8, s20, v0
	v_add_f32_e32 v9, s21, v0
	v_and_b32_e32 v9, 0x7fffffff, v9
	v_and_b32_e32 v8, 0x7fffffff, v8
	v_pk_fma_f32 v[108:109], v[166:167], v[8:9], v[140:141] op_sel_hi:[0,1,1] neg_lo:[1,0,0] neg_hi:[1,0,0]
	v_add_f32_e32 v8, s20, v6
	v_add_f32_e32 v9, s21, v6
	s_mov_b32 s20, 0xc1d00000
	s_mov_b32 s21, 0xc1d80000
	v_and_b32_e32 v9, 0x7fffffff, v9
	v_and_b32_e32 v8, 0x7fffffff, v8
	v_add_f32_e32 v7, s21, v6
	v_add_f32_e32 v6, s20, v6
	v_pk_fma_f32 v[92:93], v[166:167], v[8:9], v[124:125] op_sel_hi:[0,1,1] neg_lo:[1,0,0] neg_hi:[1,0,0]
	v_add_f32_e32 v8, s20, v0
	v_add_f32_e32 v9, s21, v0
	v_and_b32_e32 v7, 0x7fffffff, v7
	v_and_b32_e32 v6, 0x7fffffff, v6
	v_max_f32_e32 v0, v97, v81
	v_pk_fma_f32 v[94:95], v[166:167], v[6:7], v[126:127] op_sel_hi:[0,1,1] neg_lo:[1,0,0] neg_hi:[1,0,0]
	v_max3_f32 v6, v96, v80, v98
	v_max3_f32 v0, v0, v99, v83
	v_max3_f32 v6, v6, v82, v100
	v_max3_f32 v0, v0, v101, v85
	v_max3_f32 v6, v6, v84, v102
	v_max3_f32 v0, v0, v103, v87
	v_max3_f32 v6, v6, v86, v104
	v_max3_f32 v0, v0, v105, v89
	v_and_b32_e32 v9, 0x7fffffff, v9
	v_and_b32_e32 v8, 0x7fffffff, v8
	v_max3_f32 v6, v6, v88, v106
	v_max3_f32 v0, v0, v107, v91
	v_pk_fma_f32 v[110:111], v[166:167], v[8:9], v[142:143] op_sel_hi:[0,1,1] neg_lo:[1,0,0] neg_hi:[1,0,0]
	v_max3_f32 v6, v6, v90, v108
	v_max3_f32 v0, v0, v109, v93
	v_max3_f32 v6, v6, v92, v110
	v_max3_f32 v0, v0, v111, v95
	v_max3_f32 v0, v6, v94, v0
	v_mov_b32_e32 v6, v0
	s_nop 1
	v_permlane32_swap_b32_e32 v0, v6
	s_waitcnt lgkmcnt(3)
	v_mfma_f32_32x32x16_bf16 v[64:79], v[180:183], v[2:5], v[64:79]
	v_max_f32_e32 v6, v6, v6
	v_max_f32_e32 v0, v0, v0
	v_max_f32_e32 v0, v0, v6
	v_cmp_lt_f32_e32 vcc, s93, v0
	s_waitcnt lgkmcnt(2)
	v_mfma_f32_32x32x16_bf16 v[48:63], v[186:189], v[2:5], v[48:63]
	s_waitcnt lgkmcnt(1)
	v_mfma_f32_32x32x16_bf16 v[32:47], v[220:223], v[2:5], v[32:47]
	s_waitcnt lgkmcnt(0)
	v_mfma_f32_32x32x16_bf16 v[16:31], v[224:227], v[2:5], v[16:31]
	s_cbranch_vccz .LBB0_626
	v_max_f32_e32 v0, v0, v0
	v_max_f32_e32 v2, 0, v0
	v_exp_f32_e64 v0, -v2
	v_add_f32_e32 v169, v169, v2
	v_sub_f32_e32 v111, v111, v2
	v_sub_f32_e32 v110, v110, v2
	v_pk_mul_f32 v[78:79], v[78:79], v[0:1] op_sel_hi:[1,0]
	v_pk_mul_f32 v[76:77], v[76:77], v[0:1] op_sel_hi:[1,0]
	v_pk_mul_f32 v[74:75], v[74:75], v[0:1] op_sel_hi:[1,0]
	v_pk_mul_f32 v[72:73], v[72:73], v[0:1] op_sel_hi:[1,0]
	v_pk_mul_f32 v[70:71], v[70:71], v[0:1] op_sel_hi:[1,0]
	v_pk_mul_f32 v[68:69], v[68:69], v[0:1] op_sel_hi:[1,0]
	v_pk_mul_f32 v[66:67], v[66:67], v[0:1] op_sel_hi:[1,0]
	v_pk_mul_f32 v[64:65], v[64:65], v[0:1] op_sel_hi:[1,0]
	v_pk_mul_f32 v[62:63], v[62:63], v[0:1] op_sel_hi:[1,0]
	v_pk_mul_f32 v[60:61], v[60:61], v[0:1] op_sel_hi:[1,0]
	v_pk_mul_f32 v[58:59], v[58:59], v[0:1] op_sel_hi:[1,0]
	v_pk_mul_f32 v[56:57], v[56:57], v[0:1] op_sel_hi:[1,0]
	v_pk_mul_f32 v[54:55], v[54:55], v[0:1] op_sel_hi:[1,0]
	v_pk_mul_f32 v[52:53], v[52:53], v[0:1] op_sel_hi:[1,0]
	v_pk_mul_f32 v[50:51], v[50:51], v[0:1] op_sel_hi:[1,0]
	v_pk_mul_f32 v[48:49], v[48:49], v[0:1] op_sel_hi:[1,0]
	v_pk_mul_f32 v[46:47], v[0:1], v[46:47] op_sel_hi:[0,1]
	v_pk_mul_f32 v[44:45], v[0:1], v[44:45] op_sel_hi:[0,1]
	v_pk_mul_f32 v[42:43], v[0:1], v[42:43] op_sel_hi:[0,1]
	v_pk_mul_f32 v[40:41], v[0:1], v[40:41] op_sel_hi:[0,1]
	v_pk_mul_f32 v[38:39], v[0:1], v[38:39] op_sel_hi:[0,1]
	v_pk_mul_f32 v[36:37], v[0:1], v[36:37] op_sel_hi:[0,1]
	v_pk_mul_f32 v[34:35], v[0:1], v[34:35] op_sel_hi:[0,1]
	v_pk_mul_f32 v[32:33], v[0:1], v[32:33] op_sel_hi:[0,1]
	v_pk_mul_f32 v[30:31], v[0:1], v[30:31] op_sel_hi:[0,1]
	v_pk_mul_f32 v[28:29], v[0:1], v[28:29] op_sel_hi:[0,1]
	v_pk_mul_f32 v[26:27], v[0:1], v[26:27] op_sel_hi:[0,1]
	v_pk_mul_f32 v[24:25], v[0:1], v[24:25] op_sel_hi:[0,1]
	v_pk_mul_f32 v[22:23], v[0:1], v[22:23] op_sel_hi:[0,1]
	v_pk_mul_f32 v[20:21], v[0:1], v[20:21] op_sel_hi:[0,1]
	v_pk_mul_f32 v[18:19], v[0:1], v[18:19] op_sel_hi:[0,1]
	v_pk_mul_f32 v[16:17], v[0:1], v[16:17] op_sel_hi:[0,1]
	v_sub_f32_e32 v109, v109, v2
	v_sub_f32_e32 v108, v108, v2
	v_sub_f32_e32 v107, v107, v2
	v_sub_f32_e32 v106, v106, v2
	v_sub_f32_e32 v105, v105, v2
	v_sub_f32_e32 v104, v104, v2
	v_sub_f32_e32 v103, v103, v2
	v_sub_f32_e32 v102, v102, v2
	v_sub_f32_e32 v101, v101, v2
	v_sub_f32_e32 v100, v100, v2
	v_sub_f32_e32 v99, v99, v2
	v_sub_f32_e32 v98, v98, v2
	v_sub_f32_e32 v97, v97, v2
	v_sub_f32_e32 v96, v96, v2
	v_sub_f32_e32 v95, v95, v2
	v_sub_f32_e32 v94, v94, v2
	v_sub_f32_e32 v93, v93, v2
	v_sub_f32_e32 v92, v92, v2
	v_sub_f32_e32 v91, v91, v2
	v_sub_f32_e32 v90, v90, v2
	v_sub_f32_e32 v89, v89, v2
	v_sub_f32_e32 v88, v88, v2
	v_sub_f32_e32 v87, v87, v2
	v_sub_f32_e32 v86, v86, v2
	v_sub_f32_e32 v85, v85, v2
	v_sub_f32_e32 v84, v84, v2
	v_sub_f32_e32 v83, v83, v2
	v_sub_f32_e32 v82, v82, v2
	v_sub_f32_e32 v81, v81, v2
	v_sub_f32_e32 v80, v80, v2
	v_mul_f32_e32 v184, v184, v0

.LBB0_635:
	s_cmp_gt_u32 s16, 27
	s_cselect_b64 s[12:13], -1, 0
	s_mov_b64 s[34:35], -1
	s_and_b64 vcc, exec, s[12:13]
	s_cbranch_vccz .LBB0_639
	s_cmp_eq_u32 s20, 0x88000
	s_cbranch_scc1 .LBB0_638
	s_add_i32 s19, s20, 0xffff8000
	s_and_b32 s19, s19, 0xc000
	v_lshl_add_u64 v[8:9], s[10:11], 0, v[6:7]
	s_add_i32 s19, s19, s3
	v_lshl_add_u64 v[8:9], v[8:9], 0, s[74:75]
	s_mov_b32 m0, s19
	s_nop 0
	global_load_lds_dwordx4 v[8:9], off
	v_lshl_add_u64 v[10:11], v[172:173], 1, v[8:9]
	s_addk_i32 s19, 0x400
	s_mov_b32 m0, s19
	s_nop 0
	global_load_lds_dwordx4 v[10:11], off

; #define AT_ISSUE_K(tt) do { const unsigned so_ = (unsigned)(((tt) & 3) * AT_SLOT); const bf16_t* kp_ = kgp + (size_t)(tt) * 64 * DM; \
;         glds16(kp_, (unsigned)__builtin_amdgcn_readfirstlane(kdst + so_)); glds16(kp_ + kx1, (unsigned)__builtin_amdgcn_readfirstlane(kdst + so_ + 1024)); } while (0)
; #define AT_ISSUE_V(tt) do { const unsigned so_ = (unsigned)(((tt) & 3) * AT_SLOT); const bf16_t* vp_ = vgp + (tt) * 64; \
;         glds16(vp_, (unsigned)__builtin_amdgcn_readfirstlane(vdst + so_)); glds16(vp_ + vx1, (unsigned)__builtin_amdgcn_readfirstlane(vdst + so_ + 1024)); } while (0)
; #define AT_BAR(N) asm volatile("s_waitcnt vmcnt(" #N ") lgkmcnt(0)\n\ts_barrier" ::: "memory")
; template <bool STORE> __device__ __forceinline__ void attn_unit(LAS unsigned char* lds, bf16_t* Q, const bf16_t* Kg, const bf16_t* VT, const float* subg, float lam, float outscale, int unit, const int wave_s) {
;     ...
;     AT_ISSUE_K(0); AT_ISSUE_V(0); AT_ISSUE_K(1); AT_ISSUE_V(1); AT_ISSUE_K(2); AT_ISSUE_V(2); AT_ISSUE_K(3);
;     AT_BAR(8);
;     f32x16 o[4]; o[0] = f32x16{}; o[1] = f32x16{}; o[2] = f32x16{}; o[3] = f32x16{};
;     float mref = sself + 6.0f, lsum = 0.f;
;     const int koff = q * 256 + (((map * 8 + hi) ^ (q & 15)) << 4), voff = AT_VOFF + q * 128 + ((hi ^ ((q >> 1) & 7)) << 4);
;     const float qposf = (float)(qrow0 + q - 4 * hi);
;     f32x16 x0, x1, n0, n1;
.LBB0_639:
	s_andn2_b64 vcc, exec, s[34:35]
	v_lshl_add_u64 v[10:11], s[10:11], 0, v[4:5]
	v_lshl_add_u64 v[8:9], s[10:11], 0, v[6:7]
	s_cbranch_vccnz .LBB0_641
	s_add_i32 s19, s20, 0xfffec000
	s_and_b32 s19, s19, 0xc000
	s_add_i32 s19, s19, s37
	v_lshl_add_u64 v[112:113], v[10:11], 0, s[56:57]
	s_mov_b32 m0, s19
	s_nop 0
	global_load_lds_dwordx4 v[112:113], off
	s_addk_i32 s19, 0x400
	v_lshl_add_u64 v[112:113], v[170:171], 1, v[112:113]
	s_mov_b32 m0, s19
	s_nop 0
	global_load_lds_dwordx4 v[112:113], off
	s_add_i32 s19, s20, 0xffff8000
	s_and_b32 s19, s19, 0xc000
	v_lshl_add_u64 v[112:113], v[8:9], 0, s[74:75]
	s_add_i32 s19, s19, s3
	s_mov_b32 m0, s19
	s_nop 0
	global_load_lds_dwordx4 v[112:113], off
	v_lshl_add_u64 v[112:113], v[172:173], 1, v[112:113]
	s_addk_i32 s19, 0x400
	s_mov_b32 m0, s19
	s_nop 0
	global_load_lds_dwordx4 v[112:113], off
.LBB0_641:
	s_add_i32 s19, s20, 0xffff0000
	s_and_b32 s19, s19, 0xc000
	s_add_i32 s28, s19, 0
	v_add_u32_e32 v0, s28, v210
	s_sub_i32 s30, s18, 64
	ds_read_b128 v[186:189], v0
	ds_read_b128 v[216:219], v0 offset:8192
	v_cvt_f32_i32_e32 v0, s30
	v_add_u32_e32 v112, s28, v211
	ds_read_b128 v[220:223], v112
	ds_read_b128 v[224:227], v112 offset:8192
	s_add_i32 s21, s20, 0xfffec000
	v_sub_f32_e32 v0, v0, v205
	v_fma_f32 v112, v0, -v166, -v169
	v_add_f32_e32 v128, v15, v112
	v_add_f32_e32 v116, v14, v112
	v_add_f32_e32 v132, v14, v128
	v_add_f32_e32 v120, v14, v116
	v_add_f32_e32 v136, v14, v132
	v_add_f32_e32 v124, v14, v120
	v_add_f32_e32 v140, v14, v136
	v_sub_f32_e32 v113, v112, v166
	v_sub_f32_e32 v129, v128, v166
	v_sub_f32_e32 v117, v116, v166
	v_sub_f32_e32 v133, v132, v166
	v_sub_f32_e32 v121, v120, v166
	v_sub_f32_e32 v137, v136, v166
	v_sub_f32_e32 v125, v124, v166
	v_sub_f32_e32 v141, v140, v166
	v_add_f32_e32 v114, v2, v112
	v_add_f32_e32 v115, v3, v112
	v_add_f32_e32 v130, v2, v128
	v_add_f32_e32 v131, v3, v128
	v_add_f32_e32 v118, v2, v116
	v_add_f32_e32 v119, v3, v116
	v_add_f32_e32 v134, v2, v132
	v_add_f32_e32 v135, v3, v132
	v_add_f32_e32 v122, v2, v120
	v_add_f32_e32 v123, v3, v120
	v_add_f32_e32 v138, v2, v136
	v_add_f32_e32 v139, v3, v136
	v_add_f32_e32 v126, v2, v124
	v_add_f32_e32 v127, v3, v124
	v_add_f32_e32 v142, v2, v140
	v_add_f32_e32 v143, v3, v140
	s_waitcnt lgkmcnt(3)
	v_mfma_f32_32x32x16_bf16 v[112:127], v[186:189], v[144:147], v[112:127]
	v_add_u32_e32 v0, s28, v212
	ds_read_b128 v[228:231], v0
	ds_read_b128 v[232:235], v0 offset:8192
	v_add_u32_e32 v0, s28, v213
	ds_read_b128 v[186:189], v0
	ds_read_b128 v[236:239], v0 offset:8192
	s_and_b32 s21, s21, 0xc000
	v_add_u32_e32 v0, s21, v204
	ds_read_b128 v[240:243], v0
	ds_read_b128 v[244:247], v0 offset:4096
	s_waitcnt lgkmcnt(8)
	v_mfma_f32_32x32x16_bf16 v[128:143], v[216:219], v[144:147], v[128:143]
	ds_read_b128 v[216:219], v0 offset:8192
	ds_read_b128 v[248:251], v0 offset:12288
	v_exp_f32_e32 v96, v96
	v_exp_f32_e32 v165, v80
	v_exp_f32_e32 v160, v97
	v_exp_f32_e32 v0, v81
	v_exp_f32_e32 v81, v98
	v_exp_f32_e32 v97, v82
	s_waitcnt lgkmcnt(9)
	v_mfma_f32_32x32x16_bf16 v[112:127], v[220:223], v[148:151], v[112:127]
	v_exp_f32_e32 v82, v100
	v_exp_f32_e32 v98, v84
	v_exp_f32_e32 v162, v99
	v_exp_f32_e32 v164, v83
	v_exp_f32_e32 v83, v102
	v_exp_f32_e32 v99, v86
	v_exp_f32_e32 v182, v101
	s_waitcnt lgkmcnt(8)
	v_mfma_f32_32x32x16_bf16 v[128:143], v[224:227], v[148:151], v[128:143]
	v_exp_f32_e32 v190, v85
	v_exp_f32_e32 v84, v104
	v_exp_f32_e32 v100, v88
	v_exp_f32_e32 v196, v103
	v_exp_f32_e32 v198, v87
	v_exp_f32_e32 v200, v105
	v_exp_f32_e32 v220, v89
	s_waitcnt lgkmcnt(7)
	v_mfma_f32_32x32x16_bf16 v[112:127], v[228:231], v[152:155], v[112:127]
	v_exp_f32_e32 v85, v106
	v_exp_f32_e32 v101, v90
	v_exp_f32_e32 v86, v108
	v_exp_f32_e32 v102, v92
	v_exp_f32_e32 v87, v110
	v_exp_f32_e32 v103, v94
	v_exp_f32_e32 v222, v109
	s_waitcnt lgkmcnt(6)
	v_mfma_f32_32x32x16_bf16 v[128:143], v[232:235], v[152:155], v[128:143]
	v_exp_f32_e32 v224, v93
	v_exp_f32_e32 v226, v111
	v_exp_f32_e32 v228, v95
	v_add_f32_e32 v161, v96, v165
	v_add_f32_e32 v163, v81, v97
	v_add_f32_e32 v183, v82, v98
	v_add_f32_e32 v197, v83, v99
	s_waitcnt lgkmcnt(5)
	v_mfma_f32_32x32x16_bf16 v[112:127], v[186:189], v[156:159], v[112:127]
	v_exp_f32_e32 v186, v107
	v_exp_f32_e32 v188, v91
	v_add_f32_e32 v201, v84, v100
	v_add_f32_e32 v187, v85, v101
	v_add_f32_e32 v223, v86, v102
	v_add_f32_e32 v227, v87, v103
	v_cvt_pk_bf16_f32 v80, v96, v160
	s_waitcnt lgkmcnt(4)
	v_mfma_f32_32x32x16_bf16 v[128:143], v[236:239], v[156:159], v[128:143]
	v_cvt_pk_bf16_f32 v81, v81, v162
	v_cvt_pk_bf16_f32 v82, v82, v182
	v_cvt_pk_bf16_f32 v83, v83, v196
	v_cvt_pk_bf16_f32 v84, v84, v200
	v_cvt_pk_bf16_f32 v85, v85, v186
	v_cvt_pk_bf16_f32 v86, v86, v222
	v_cvt_pk_bf16_f32 v87, v87, v226
	v_cvt_pk_bf16_f32 v88, v165, v0
	v_cvt_pk_bf16_f32 v89, v97, v164
	v_cvt_pk_bf16_f32 v90, v98, v190
	v_cvt_pk_bf16_f32 v91, v99, v198
	v_cvt_pk_bf16_f32 v92, v100, v220
	v_cvt_pk_bf16_f32 v93, v101, v188
	v_cvt_pk_bf16_f32 v94, v102, v224
	v_cvt_pk_bf16_f32 v95, v103, v228
	v_add_f32_e32 v160, v160, v0
	v_add_f32_e32 v161, v161, v1
	v_add_u32_e32 v108, s21, v167
	v_add_f32_e32 v165, v160, v161
	v_add_f32_e32 v160, v162, v164
	v_add_f32_e32 v161, v163, v165
	s_waitcnt lgkmcnt(3)
	v_mfma_f32_32x32x16_bf16 v[64:79], v[240:243], v[80:83], v[64:79]
	v_add_f32_e32 v191, v160, v161
	v_add_f32_e32 v160, v182, v190
	v_add_f32_e32 v161, v183, v191
	ds_read_b128 v[96:99], v108
	ds_read_b128 v[100:103], v108 offset:4096
	ds_read_b128 v[104:107], v108 offset:8192
	ds_read_b128 v[108:111], v108 offset:12288
	v_add_f32_e32 v199, v160, v161
	v_add_f32_e32 v160, v196, v198
	v_add_f32_e32 v161, v197, v199
	s_waitcnt lgkmcnt(6)
	v_mfma_f32_32x32x16_bf16 v[48:63], v[244:247], v[80:83], v[48:63]
	v_add_f32_e32 v221, v160, v161
	v_add_f32_e32 v160, v200, v220
	v_add_f32_e32 v161, v201, v221
	s_nop 0
	v_add_f32_e32 v189, v160, v161
	v_add_f32_e32 v160, v186, v188
	v_add_f32_e32 v161, v187, v189
	s_waitcnt lgkmcnt(5)
	v_mfma_f32_32x32x16_bf16 v[32:47], v[216:219], v[80:83], v[32:47]
	v_add_f32_e32 v225, v160, v161
	v_add_f32_e32 v160, v222, v224
	v_add_f32_e32 v161, v223, v225
	s_nop 0
	v_add_f32_e32 v229, v160, v161
	v_add_f32_e32 v160, v226, v228
	v_add_f32_e32 v161, v227, v229
	s_waitcnt lgkmcnt(4)
	v_mfma_f32_32x32x16_bf16 v[16:31], v[248:251], v[80:83], v[16:31]
	v_add_f32_e32 v0, v160, v161
	v_add_f32_e32 v178, v184, v0
	s_waitcnt lgkmcnt(3)
	v_mfma_f32_32x32x16_bf16 v[64:79], v[96:99], v[84:87], v[64:79]
	v_add_u32_e32 v0, s21, v168
	s_waitcnt lgkmcnt(2)
	v_mfma_f32_32x32x16_bf16 v[48:63], v[100:103], v[84:87], v[48:63]
	s_waitcnt lgkmcnt(1)
	v_mfma_f32_32x32x16_bf16 v[32:47], v[104:107], v[84:87], v[32:47]
	ds_read_b128 v[80:83], v0
	ds_read_b128 v[96:99], v0 offset:4096
	ds_read_b128 v[100:103], v0 offset:8192
	ds_read_b128 v[104:107], v0 offset:12288
	s_waitcnt lgkmcnt(4)
	v_mfma_f32_32x32x16_bf16 v[16:31], v[108:111], v[84:87], v[16:31]
	v_add_u32_e32 v0, s21, v180
	ds_read_b128 v[84:87], v0
	ds_read_b128 v[108:111], v0 offset:4096
	s_waitcnt lgkmcnt(5)
	v_mfma_f32_32x32x16_bf16 v[64:79], v[80:83], v[88:91], v[64:79]
	ds_read_b128 v[80:83], v0 offset:8192
	ds_read_b128 v[182:185], v0 offset:12288
	v_max_f32_e32 v0, v113, v113
	v_max_f32_e32 v160, v129, v129
	v_max_f32_e32 v0, v0, v160
	v_max3_f32 v160, v112, v128, v114
	v_max3_f32 v0, v0, v115, v131
	v_max3_f32 v160, v160, v130, v116
	v_max3_f32 v0, v0, v117, v133
	s_waitcnt lgkmcnt(6)
	v_mfma_f32_32x32x16_bf16 v[48:63], v[96:99], v[88:91], v[48:63]
	v_max3_f32 v96, v160, v132, v118
	v_max3_f32 v0, v0, v119, v135
	v_max3_f32 v96, v96, v134, v120
	v_max3_f32 v0, v0, v121, v137
	v_max3_f32 v96, v96, v136, v122
	v_max3_f32 v0, v0, v123, v139
	v_max3_f32 v96, v96, v138, v124
	s_waitcnt lgkmcnt(5)
	v_mfma_f32_32x32x16_bf16 v[32:47], v[100:103], v[88:91], v[32:47]
	v_max3_f32 v0, v0, v125, v141
	v_max3_f32 v96, v96, v140, v126
	v_max3_f32 v0, v0, v127, v143
	v_max3_f32 v0, v96, v142, v0
	v_mov_b32_e32 v96, v0
	s_nop 1
	v_permlane32_swap_b32_e32 v0, v96
	s_waitcnt lgkmcnt(4)
	v_mfma_f32_32x32x16_bf16 v[16:31], v[104:107], v[88:91], v[16:31]
	s_waitcnt lgkmcnt(3)
	v_mfma_f32_32x32x16_bf16 v[64:79], v[84:87], v[92:95], v[64:79]
	v_max_f32_e32 v0, v0, v0
	s_waitcnt lgkmcnt(2)
	v_mfma_f32_32x32x16_bf16 v[48:63], v[108:111], v[92:95], v[48:63]
	s_waitcnt lgkmcnt(1)
	v_mfma_f32_32x32x16_bf16 v[32:47], v[80:83], v[92:95], v[32:47]
	v_max_f32_e32 v80, v96, v96
	v_max_f32_e32 v0, v0, v80
	v_cmp_lt_f32_e32 vcc, s93, v0
	s_waitcnt lgkmcnt(0)
	v_mfma_f32_32x32x16_bf16 v[16:31], v[182:185], v[92:95], v[16:31]
	s_cbranch_vccz .LBB0_643
	v_max_f32_e32 v0, v0, v0
	v_max_f32_e32 v80, 0, v0
	v_exp_f32_e64 v0, -v80
	v_add_f32_e32 v169, v169, v80
	v_sub_f32_e32 v127, v127, v80
	v_sub_f32_e32 v126, v126, v80
	v_pk_mul_f32 v[78:79], v[78:79], v[0:1] op_sel_hi:[1,0]
	v_pk_mul_f32 v[76:77], v[76:77], v[0:1] op_sel_hi:[1,0]
	v_pk_mul_f32 v[74:75], v[74:75], v[0:1] op_sel_hi:[1,0]
	v_pk_mul_f32 v[72:73], v[72:73], v[0:1] op_sel_hi:[1,0]
	v_pk_mul_f32 v[70:71], v[70:71], v[0:1] op_sel_hi:[1,0]
	v_pk_mul_f32 v[68:69], v[68:69], v[0:1] op_sel_hi:[1,0]
	v_pk_mul_f32 v[66:67], v[66:67], v[0:1] op_sel_hi:[1,0]
	v_pk_mul_f32 v[64:65], v[64:65], v[0:1] op_sel_hi:[1,0]
	v_pk_mul_f32 v[62:63], v[62:63], v[0:1] op_sel_hi:[1,0]
	v_pk_mul_f32 v[60:61], v[60:61], v[0:1] op_sel_hi:[1,0]
	v_pk_mul_f32 v[58:59], v[58:59], v[0:1] op_sel_hi:[1,0]
	v_pk_mul_f32 v[56:57], v[56:57], v[0:1] op_sel_hi:[1,0]
	v_pk_mul_f32 v[54:55], v[54:55], v[0:1] op_sel_hi:[1,0]
	v_pk_mul_f32 v[52:53], v[52:53], v[0:1] op_sel_hi:[1,0]
	v_pk_mul_f32 v[50:51], v[50:51], v[0:1] op_sel_hi:[1,0]
	v_pk_mul_f32 v[48:49], v[48:49], v[0:1] op_sel_hi:[1,0]
	v_pk_mul_f32 v[46:47], v[0:1], v[46:47] op_sel_hi:[0,1]
	v_pk_mul_f32 v[44:45], v[0:1], v[44:45] op_sel_hi:[0,1]
	v_pk_mul_f32 v[42:43], v[0:1], v[42:43] op_sel_hi:[0,1]
	v_pk_mul_f32 v[40:41], v[0:1], v[40:41] op_sel_hi:[0,1]
	v_pk_mul_f32 v[38:39], v[0:1], v[38:39] op_sel_hi:[0,1]
	v_pk_mul_f32 v[36:37], v[0:1], v[36:37] op_sel_hi:[0,1]
	v_pk_mul_f32 v[34:35], v[0:1], v[34:35] op_sel_hi:[0,1]
	v_pk_mul_f32 v[32:33], v[0:1], v[32:33] op_sel_hi:[0,1]
	v_pk_mul_f32 v[30:31], v[0:1], v[30:31] op_sel_hi:[0,1]
	v_pk_mul_f32 v[28:29], v[0:1], v[28:29] op_sel_hi:[0,1]
	v_pk_mul_f32 v[26:27], v[0:1], v[26:27] op_sel_hi:[0,1]
	v_pk_mul_f32 v[24:25], v[0:1], v[24:25] op_sel_hi:[0,1]
	v_pk_mul_f32 v[22:23], v[0:1], v[22:23] op_sel_hi:[0,1]
	v_pk_mul_f32 v[20:21], v[0:1], v[20:21] op_sel_hi:[0,1]
	v_pk_mul_f32 v[18:19], v[0:1], v[18:19] op_sel_hi:[0,1]
	v_pk_mul_f32 v[16:17], v[0:1], v[16:17] op_sel_hi:[0,1]
	v_sub_f32_e32 v125, v125, v80
	v_sub_f32_e32 v124, v124, v80
	v_sub_f32_e32 v123, v123, v80
	v_sub_f32_e32 v122, v122, v80
	v_sub_f32_e32 v121, v121, v80
	v_sub_f32_e32 v120, v120, v80
	v_sub_f32_e32 v119, v119, v80
	v_sub_f32_e32 v118, v118, v80
	v_sub_f32_e32 v117, v117, v80
	v_sub_f32_e32 v116, v116, v80
	v_sub_f32_e32 v115, v115, v80
	v_sub_f32_e32 v114, v114, v80
	v_sub_f32_e32 v113, v113, v80
	v_sub_f32_e32 v112, v112, v80
	v_sub_f32_e32 v143, v143, v80
	v_sub_f32_e32 v142, v142, v80
	v_sub_f32_e32 v141, v141, v80
	v_sub_f32_e32 v140, v140, v80
	v_sub_f32_e32 v139, v139, v80
	v_sub_f32_e32 v138, v138, v80
	v_sub_f32_e32 v137, v137, v80
	v_sub_f32_e32 v136, v136, v80
	v_sub_f32_e32 v135, v135, v80
	v_sub_f32_e32 v134, v134, v80
	v_sub_f32_e32 v133, v133, v80
	v_sub_f32_e32 v132, v132, v80
	v_sub_f32_e32 v131, v131, v80
	v_sub_f32_e32 v130, v130, v80
	v_sub_f32_e32 v129, v129, v80
	v_sub_f32_e32 v128, v128, v80
	v_mul_f32_e32 v178, v178, v0

.LBB0_647:
	s_cmp_gt_u32 s16, 26
	s_cselect_b64 s[34:35], -1, 0
	s_mov_b64 s[40:41], -1
	s_and_b64 vcc, exec, s[34:35]
	s_cbranch_vccz .LBB0_651
	s_cmp_lg_u32 s20, 0x80000
	s_cbranch_scc1 .LBB0_650
	s_add_i32 s28, s37, 0x1c000
	s_mov_b32 m0, s28
	s_nop 0
	global_load_lds_dwordx4 v[174:175], off
	s_add_i32 s28, s37, 0x1c400
	s_mov_b32 m0, s28
	s_nop 0
	global_load_lds_dwordx4 v[176:177], off

; #define AT_ISSUE_K(tt) do { const unsigned so_ = (unsigned)(((tt) & 3) * AT_SLOT); const bf16_t* kp_ = kgp + (size_t)(tt) * 64 * DM; \
;         glds16(kp_, (unsigned)__builtin_amdgcn_readfirstlane(kdst + so_)); glds16(kp_ + kx1, (unsigned)__builtin_amdgcn_readfirstlane(kdst + so_ + 1024)); } while (0)
; #define AT_ISSUE_V(tt) do { const unsigned so_ = (unsigned)(((tt) & 3) * AT_SLOT); const bf16_t* vp_ = vgp + (tt) * 64; \
;         glds16(vp_, (unsigned)__builtin_amdgcn_readfirstlane(vdst + so_)); glds16(vp_ + vx1, (unsigned)__builtin_amdgcn_readfirstlane(vdst + so_ + 1024)); } while (0)
; #define AT_BAR(N) asm volatile("s_waitcnt vmcnt(" #N ") lgkmcnt(0)\n\ts_barrier" ::: "memory")
; template <bool STORE> __device__ __forceinline__ void attn_unit(LAS unsigned char* lds, bf16_t* Q, const bf16_t* Kg, const bf16_t* VT, const float* subg, float lam, float outscale, int unit, const int wave_s) {
;     ...
;     AT_ISSUE_K(0); AT_ISSUE_V(0); AT_ISSUE_K(1); AT_ISSUE_V(1); AT_ISSUE_K(2); AT_ISSUE_V(2); AT_ISSUE_K(3);
;     AT_BAR(8);
;     f32x16 o[4]; o[0] = f32x16{}; o[1] = f32x16{}; o[2] = f32x16{}; o[3] = f32x16{};
;     float mref = sself + 6.0f, lsum = 0.f;
;     const int koff = q * 256 + (((map * 8 + hi) ^ (q & 15)) << 4), voff = AT_VOFF + q * 128 + ((hi ^ ((q >> 1) & 7)) << 4);
;     const float qposf = (float)(qrow0 + q - 4 * hi);
;     f32x16 x0, x1, n0, n1;
.LBB0_651:
	s_andn2_b64 vcc, exec, s[40:41]
	s_cbranch_vccnz .LBB0_653
	s_and_b32 s28, s20, 0xc000
	s_mov_b64 s[40:41], 0x8da0000
	v_lshl_add_u64 v[10:11], v[10:11], 0, s[40:41]
	s_add_i32 s28, s28, s37
	s_mov_b32 m0, s28
	s_nop 0
	global_load_lds_dwordx4 v[10:11], off
	v_lshl_add_u64 v[10:11], v[170:171], 1, v[10:11]
	s_addk_i32 s28, 0x400
	s_mov_b32 m0, s28
	s_nop 0
	global_load_lds_dwordx4 v[10:11], off
	v_lshl_add_u64 v[8:9], v[8:9], 0, s[88:89]
	s_add_i32 s21, s21, s3
	s_mov_b32 m0, s21
	s_nop 0
	global_load_lds_dwordx4 v[8:9], off
	v_lshl_add_u64 v[8:9], v[172:173], 1, v[8:9]
	s_addk_i32 s21, 0x400
	s_mov_b32 m0, s21
	s_nop 0
	global_load_lds_dwordx4 v[8:9], off
.LBB0_653:
	s_add_i32 s21, s20, 0xffff4000
	s_and_b32 s21, s21, 0xc000
	s_add_i32 s21, s21, 0
	v_add_u32_e32 v0, s21, v210
	ds_read_b128 v[8:11], v0
	ds_read_b128 v[182:185], v0 offset:8192
	v_cvt_f32_i32_e32 v0, s18
	v_add_u32_e32 v80, s21, v211
	ds_read_b128 v[186:189], v80
	ds_read_b128 v[216:219], v80 offset:8192
	v_sub_f32_e32 v0, v0, v205
	v_fma_f32 v96, v0, -v166, -v169
	v_add_f32_e32 v80, v15, v96
	v_add_f32_e32 v100, v14, v96
	v_add_f32_e32 v84, v14, v80
	v_add_f32_e32 v104, v14, v100
	v_add_f32_e32 v88, v14, v84
	v_add_f32_e32 v108, v14, v104
	v_add_f32_e32 v92, v14, v88
	v_sub_f32_e32 v97, v96, v166
	v_sub_f32_e32 v81, v80, v166
	v_sub_f32_e32 v101, v100, v166
	v_sub_f32_e32 v85, v84, v166
	v_sub_f32_e32 v105, v104, v166
	v_sub_f32_e32 v89, v88, v166
	v_sub_f32_e32 v109, v108, v166
	v_sub_f32_e32 v93, v92, v166
	v_add_f32_e32 v98, v2, v96
	v_add_f32_e32 v99, v3, v96
	v_add_f32_e32 v82, v2, v80
	v_add_f32_e32 v83, v3, v80
	v_add_f32_e32 v102, v2, v100
	v_add_f32_e32 v103, v3, v100
	v_add_f32_e32 v86, v2, v84
	v_add_f32_e32 v87, v3, v84
	v_add_f32_e32 v106, v2, v104
	v_add_f32_e32 v107, v3, v104
	v_add_f32_e32 v90, v2, v88
	v_add_f32_e32 v91, v3, v88
	v_add_f32_e32 v110, v2, v108
	v_add_f32_e32 v111, v3, v108
	v_add_f32_e32 v94, v2, v92
	v_add_f32_e32 v95, v3, v92
	s_waitcnt lgkmcnt(3)
	v_mfma_f32_32x32x16_bf16 v[96:111], v[8:11], v[144:147], v[96:111]
	v_add_u32_e32 v0, s21, v212
	ds_read_b128 v[220:223], v0
	ds_read_b128 v[224:227], v0 offset:8192
	v_add_u32_e32 v0, s21, v213
	ds_read_b128 v[228:231], v0
	ds_read_b128 v[232:235], v0 offset:8192
	v_add_u32_e32 v0, s19, v204
	ds_read_b128 v[8:11], v0
	ds_read_b128 v[236:239], v0 offset:4096
	ds_read_b128 v[240:243], v0 offset:8192
	ds_read_b128 v[244:247], v0 offset:12288
	s_waitcnt lgkmcnt(10)
	v_mfma_f32_32x32x16_bf16 v[80:95], v[182:185], v[144:147], v[80:95]
	v_exp_f32_e32 v112, v112
	v_exp_f32_e32 v128, v128
	v_exp_f32_e32 v0, v113
	v_exp_f32_e32 v160, v129
	v_exp_f32_e32 v113, v114
	v_exp_f32_e32 v129, v130
	v_exp_f32_e32 v114, v116
	s_waitcnt lgkmcnt(9)
	v_mfma_f32_32x32x16_bf16 v[96:111], v[186:189], v[148:151], v[96:111]
	v_exp_f32_e32 v130, v132
	v_exp_f32_e32 v164, v115
	v_exp_f32_e32 v162, v131
	v_exp_f32_e32 v115, v118
	v_exp_f32_e32 v131, v134
	v_exp_f32_e32 v184, v117
	v_exp_f32_e32 v182, v133
	s_waitcnt lgkmcnt(8)
	v_mfma_f32_32x32x16_bf16 v[80:95], v[216:219], v[148:151], v[80:95]
	v_exp_f32_e32 v188, v119
	v_exp_f32_e32 v186, v135
	v_exp_f32_e32 v116, v120
	v_exp_f32_e32 v132, v136
	v_exp_f32_e32 v117, v122
	v_exp_f32_e32 v133, v138
	v_exp_f32_e32 v196, v121
	s_waitcnt lgkmcnt(7)
	v_mfma_f32_32x32x16_bf16 v[96:111], v[220:223], v[152:155], v[96:111]
	v_exp_f32_e32 v190, v137
	v_exp_f32_e32 v118, v124
	v_exp_f32_e32 v134, v140
	v_exp_f32_e32 v200, v123
	v_exp_f32_e32 v198, v139
	v_exp_f32_e32 v119, v126
	v_exp_f32_e32 v135, v142
	s_waitcnt lgkmcnt(6)
	v_mfma_f32_32x32x16_bf16 v[80:95], v[224:227], v[152:155], v[80:95]
	v_exp_f32_e32 v218, v125
	v_exp_f32_e32 v216, v141
	v_exp_f32_e32 v222, v127
	v_exp_f32_e32 v220, v143
	v_add_f32_e32 v161, v128, v112
	v_add_f32_e32 v163, v129, v113
	v_add_f32_e32 v183, v130, v114
	s_waitcnt lgkmcnt(5)
	v_mfma_f32_32x32x16_bf16 v[96:111], v[228:231], v[156:159], v[96:111]
	v_add_f32_e32 v187, v131, v115
	v_add_f32_e32 v191, v132, v116
	v_add_f32_e32 v199, v133, v117
	v_add_f32_e32 v217, v134, v118
	v_add_f32_e32 v221, v135, v119
	v_cvt_pk_bf16_f32 v112, v112, v0
	v_cvt_pk_bf16_f32 v113, v113, v164
	s_waitcnt lgkmcnt(4)
	v_mfma_f32_32x32x16_bf16 v[80:95], v[232:235], v[156:159], v[80:95]
	v_cvt_pk_bf16_f32 v114, v114, v184
	v_cvt_pk_bf16_f32 v115, v115, v188
	v_cvt_pk_bf16_f32 v116, v116, v196
	v_cvt_pk_bf16_f32 v117, v117, v200
	v_cvt_pk_bf16_f32 v118, v118, v218
	v_cvt_pk_bf16_f32 v119, v119, v222
	v_cvt_pk_bf16_f32 v120, v128, v160
	v_cvt_pk_bf16_f32 v121, v129, v162
	v_cvt_pk_bf16_f32 v122, v130, v182
	v_cvt_pk_bf16_f32 v123, v131, v186
	v_cvt_pk_bf16_f32 v124, v132, v190
	v_cvt_pk_bf16_f32 v125, v133, v198
	v_cvt_pk_bf16_f32 v126, v134, v216
	v_cvt_pk_bf16_f32 v127, v135, v220
	v_add_f32_e32 v160, v160, v0
	v_add_f32_e32 v161, v161, v1
	s_waitcnt lgkmcnt(3)
	v_mfma_f32_32x32x16_bf16 v[64:79], v[8:11], v[112:115], v[64:79]
	v_add_f32_e32 v165, v160, v161
	v_add_f32_e32 v8, v162, v164
	v_add_f32_e32 v9, v163, v165
	v_add_u32_e32 v140, s19, v167
	v_add_f32_e32 v185, v8, v9
	v_add_f32_e32 v8, v182, v184
	v_add_f32_e32 v9, v183, v185
	s_waitcnt lgkmcnt(2)
	v_mfma_f32_32x32x16_bf16 v[48:63], v[236:239], v[112:115], v[48:63]
	v_add_f32_e32 v189, v8, v9
	v_add_f32_e32 v8, v186, v188
	v_add_f32_e32 v9, v187, v189
	ds_read_b128 v[128:131], v140
	ds_read_b128 v[132:135], v140 offset:4096
	ds_read_b128 v[136:139], v140 offset:8192
	ds_read_b128 v[140:143], v140 offset:12288
	v_add_f32_e32 v197, v8, v9
	v_add_f32_e32 v8, v190, v196
	v_add_f32_e32 v9, v191, v197
	s_waitcnt lgkmcnt(5)
	v_mfma_f32_32x32x16_bf16 v[32:47], v[240:243], v[112:115], v[32:47]
	v_add_f32_e32 v201, v8, v9
	v_add_f32_e32 v8, v198, v200
	v_add_f32_e32 v9, v199, v201
	s_nop 0
	v_add_f32_e32 v219, v8, v9
	v_add_f32_e32 v8, v216, v218
	v_add_f32_e32 v9, v217, v219
	s_waitcnt lgkmcnt(4)
	v_mfma_f32_32x32x16_bf16 v[16:31], v[244:247], v[112:115], v[16:31]
	v_add_f32_e32 v223, v8, v9
	v_add_f32_e32 v8, v220, v222
	v_add_f32_e32 v9, v221, v223
	s_nop 0
	v_add_f32_e32 v0, v8, v9
	v_add_f32_e32 v184, v178, v0
	s_waitcnt lgkmcnt(3)
	v_mfma_f32_32x32x16_bf16 v[64:79], v[128:131], v[116:119], v[64:79]
	v_add_u32_e32 v0, s19, v168
	s_waitcnt lgkmcnt(2)
	v_mfma_f32_32x32x16_bf16 v[48:63], v[132:135], v[116:119], v[48:63]
	ds_read_b128 v[8:11], v0
	ds_read_b128 v[112:115], v0 offset:4096
	ds_read_b128 v[128:131], v0 offset:8192
	ds_read_b128 v[132:135], v0 offset:12288
	s_waitcnt lgkmcnt(5)
	v_mfma_f32_32x32x16_bf16 v[32:47], v[136:139], v[116:119], v[32:47]
	s_waitcnt lgkmcnt(4)
	v_mfma_f32_32x32x16_bf16 v[16:31], v[140:143], v[116:119], v[16:31]
	v_add_u32_e32 v0, s19, v180
	ds_read_b128 v[116:119], v0
	ds_read_b128 v[136:139], v0 offset:4096
	s_waitcnt lgkmcnt(5)
	v_mfma_f32_32x32x16_bf16 v[64:79], v[8:11], v[120:123], v[64:79]
	ds_read_b128 v[8:11], v0 offset:8192
	ds_read_b128 v[140:143], v0 offset:12288
	v_max_f32_e32 v0, v97, v97
	v_max_f32_e32 v160, v81, v81
	v_max_f32_e32 v0, v0, v160
	v_max3_f32 v160, v96, v80, v98
	v_max3_f32 v0, v0, v99, v83
	v_max3_f32 v160, v160, v82, v100
	v_max3_f32 v0, v0, v101, v85
	s_waitcnt lgkmcnt(6)
	v_mfma_f32_32x32x16_bf16 v[48:63], v[112:115], v[120:123], v[48:63]
	v_max3_f32 v112, v160, v84, v102
	v_max3_f32 v0, v0, v103, v87
	v_max3_f32 v112, v112, v86, v104
	v_max3_f32 v0, v0, v105, v89
	v_max3_f32 v112, v112, v88, v106
	v_max3_f32 v0, v0, v107, v91
	v_max3_f32 v112, v112, v90, v108
	s_waitcnt lgkmcnt(5)
	v_mfma_f32_32x32x16_bf16 v[32:47], v[128:131], v[120:123], v[32:47]
	v_max3_f32 v0, v0, v109, v93
	v_max3_f32 v112, v112, v92, v110
	v_max3_f32 v0, v0, v111, v95
	v_max3_f32 v0, v112, v94, v0
	v_mov_b32_e32 v112, v0
	s_nop 1
	v_permlane32_swap_b32_e32 v0, v112
	s_waitcnt lgkmcnt(4)
	v_mfma_f32_32x32x16_bf16 v[16:31], v[132:135], v[120:123], v[16:31]
	s_waitcnt lgkmcnt(3)
	v_mfma_f32_32x32x16_bf16 v[64:79], v[116:119], v[124:127], v[64:79]
	v_max_f32_e32 v0, v0, v0
	s_waitcnt lgkmcnt(2)
	v_mfma_f32_32x32x16_bf16 v[48:63], v[136:139], v[124:127], v[48:63]
	s_waitcnt lgkmcnt(1)
	v_mfma_f32_32x32x16_bf16 v[32:47], v[8:11], v[124:127], v[32:47]
	v_max_f32_e32 v8, v112, v112
	v_max_f32_e32 v0, v0, v8
	v_cmp_lt_f32_e32 vcc, s93, v0
	s_waitcnt lgkmcnt(0)
	v_mfma_f32_32x32x16_bf16 v[16:31], v[140:143], v[124:127], v[16:31]
	s_cbranch_vccz .LBB0_655
	v_max_f32_e32 v0, v0, v0
	v_max_f32_e32 v8, 0, v0
	v_exp_f32_e64 v0, -v8
	v_add_f32_e32 v169, v169, v8
	v_sub_f32_e32 v111, v111, v8
	v_sub_f32_e32 v110, v110, v8
	v_pk_mul_f32 v[78:79], v[78:79], v[0:1] op_sel_hi:[1,0]
	v_pk_mul_f32 v[76:77], v[76:77], v[0:1] op_sel_hi:[1,0]
	v_pk_mul_f32 v[74:75], v[74:75], v[0:1] op_sel_hi:[1,0]
	v_pk_mul_f32 v[72:73], v[72:73], v[0:1] op_sel_hi:[1,0]
	v_pk_mul_f32 v[70:71], v[70:71], v[0:1] op_sel_hi:[1,0]
	v_pk_mul_f32 v[68:69], v[68:69], v[0:1] op_sel_hi:[1,0]
	v_pk_mul_f32 v[66:67], v[66:67], v[0:1] op_sel_hi:[1,0]
	v_pk_mul_f32 v[64:65], v[64:65], v[0:1] op_sel_hi:[1,0]
	v_pk_mul_f32 v[62:63], v[62:63], v[0:1] op_sel_hi:[1,0]
	v_pk_mul_f32 v[60:61], v[60:61], v[0:1] op_sel_hi:[1,0]
	v_pk_mul_f32 v[58:59], v[58:59], v[0:1] op_sel_hi:[1,0]
	v_pk_mul_f32 v[56:57], v[56:57], v[0:1] op_sel_hi:[1,0]
	v_pk_mul_f32 v[54:55], v[54:55], v[0:1] op_sel_hi:[1,0]
	v_pk_mul_f32 v[52:53], v[52:53], v[0:1] op_sel_hi:[1,0]
	v_pk_mul_f32 v[50:51], v[50:51], v[0:1] op_sel_hi:[1,0]
	v_pk_mul_f32 v[48:49], v[48:49], v[0:1] op_sel_hi:[1,0]
	v_pk_mul_f32 v[46:47], v[0:1], v[46:47] op_sel_hi:[0,1]
	v_pk_mul_f32 v[44:45], v[0:1], v[44:45] op_sel_hi:[0,1]
	v_pk_mul_f32 v[42:43], v[0:1], v[42:43] op_sel_hi:[0,1]
	v_pk_mul_f32 v[40:41], v[0:1], v[40:41] op_sel_hi:[0,1]
	v_pk_mul_f32 v[38:39], v[0:1], v[38:39] op_sel_hi:[0,1]
	v_pk_mul_f32 v[36:37], v[0:1], v[36:37] op_sel_hi:[0,1]
	v_pk_mul_f32 v[34:35], v[0:1], v[34:35] op_sel_hi:[0,1]
	v_pk_mul_f32 v[32:33], v[0:1], v[32:33] op_sel_hi:[0,1]
	v_pk_mul_f32 v[30:31], v[0:1], v[30:31] op_sel_hi:[0,1]
	v_pk_mul_f32 v[28:29], v[0:1], v[28:29] op_sel_hi:[0,1]
	v_pk_mul_f32 v[26:27], v[0:1], v[26:27] op_sel_hi:[0,1]
	v_pk_mul_f32 v[24:25], v[0:1], v[24:25] op_sel_hi:[0,1]
	v_pk_mul_f32 v[22:23], v[0:1], v[22:23] op_sel_hi:[0,1]
	v_pk_mul_f32 v[20:21], v[0:1], v[20:21] op_sel_hi:[0,1]
	v_pk_mul_f32 v[18:19], v[0:1], v[18:19] op_sel_hi:[0,1]
	v_pk_mul_f32 v[16:17], v[0:1], v[16:17] op_sel_hi:[0,1]
	v_sub_f32_e32 v109, v109, v8
	v_sub_f32_e32 v108, v108, v8
	v_sub_f32_e32 v107, v107, v8
	v_sub_f32_e32 v106, v106, v8
	v_sub_f32_e32 v105, v105, v8
	v_sub_f32_e32 v104, v104, v8
	v_sub_f32_e32 v103, v103, v8
	v_sub_f32_e32 v102, v102, v8
	v_sub_f32_e32 v101, v101, v8
	v_sub_f32_e32 v100, v100, v8
	v_sub_f32_e32 v99, v99, v8
	v_sub_f32_e32 v98, v98, v8
	v_sub_f32_e32 v97, v97, v8
	v_sub_f32_e32 v96, v96, v8
	v_sub_f32_e32 v95, v95, v8
	v_sub_f32_e32 v94, v94, v8
	v_sub_f32_e32 v93, v93, v8
	v_sub_f32_e32 v92, v92, v8
	v_sub_f32_e32 v91, v91, v8
	v_sub_f32_e32 v90, v90, v8
	v_sub_f32_e32 v89, v89, v8
	v_sub_f32_e32 v88, v88, v8
	v_sub_f32_e32 v87, v87, v8
	v_sub_f32_e32 v86, v86, v8
	v_sub_f32_e32 v85, v85, v8
	v_sub_f32_e32 v84, v84, v8
	v_sub_f32_e32 v83, v83, v8
	v_sub_f32_e32 v82, v82, v8
	v_sub_f32_e32 v81, v81, v8
	v_sub_f32_e32 v80, v80, v8
	v_mul_f32_e32 v184, v184, v0

.LBB0_661:
	s_andn2_b64 vcc, exec, s[12:13]
	s_cbranch_vccnz .LBB0_665
	v_sub_f32_e32 v0, 0x44f80000, v205
	v_fma_f32 v112, v0, -v166, -v169
	v_fma_f32 v0, 2.0, v2, v13
	ds_read_b128 v[4:7], v208 offset:49152
	ds_read_b128 v[8:11], v208 offset:57344
	ds_read_b128 v[170:173], v209 offset:49152
	ds_read_b128 v[174:177], v209 offset:57344
	v_fmac_f32_e32 v0, 2.0, v13
	v_fma_f32 v128, 2.0, v0, v112
	v_fma_f32 v116, 2.0, v13, v112
	v_fma_f32 v132, 2.0, v13, v128
	v_fma_f32 v120, 2.0, v13, v116
	v_fma_f32 v136, 2.0, v13, v132
	v_fma_f32 v124, 2.0, v13, v120
	v_fma_f32 v140, 2.0, v13, v136
	v_sub_f32_e32 v113, v112, v166
	v_sub_f32_e32 v129, v128, v166
	v_sub_f32_e32 v117, v116, v166
	v_sub_f32_e32 v133, v132, v166
	v_sub_f32_e32 v121, v120, v166
	v_sub_f32_e32 v137, v136, v166
	v_sub_f32_e32 v125, v124, v166
	v_sub_f32_e32 v141, v140, v166
	v_add_f32_e32 v114, v2, v112
	v_add_f32_e32 v115, v3, v112
	v_add_f32_e32 v130, v2, v128
	v_add_f32_e32 v131, v3, v128
	v_add_f32_e32 v118, v2, v116
	v_add_f32_e32 v119, v3, v116
	v_add_f32_e32 v134, v2, v132
	v_add_f32_e32 v135, v3, v132
	v_add_f32_e32 v122, v2, v120
	v_add_f32_e32 v123, v3, v120
	v_add_f32_e32 v138, v2, v136
	v_add_f32_e32 v139, v3, v136
	v_add_f32_e32 v126, v2, v124
	v_add_f32_e32 v127, v3, v124
	v_add_f32_e32 v142, v2, v140
	v_add_f32_e32 v143, v3, v140
	s_waitcnt lgkmcnt(3)
	v_mfma_f32_32x32x16_bf16 v[112:127], v[4:7], v[144:147], v[112:127]
	ds_read_b128 v[166:169], v206 offset:49152
	ds_read_b128 v[180:183], v206 offset:57344
	ds_read_b128 v[186:189], v207 offset:49152
	ds_read_b128 v[206:209], v207 offset:57344
	s_add_i32 s12, 0, 0x8000
	v_add_u32_e32 v0, s12, v214
	ds_read_b128 v[2:5], v0
	ds_read_b128 v[210:213], v0 offset:4096
	ds_read_b128 v[214:217], v0 offset:8192
	ds_read_b128 v[218:221], v0 offset:12288
	v_exp_f32_e32 v6, v96
	v_exp_f32_e32 v13, v80
	v_exp_f32_e32 v7, v98
	s_waitcnt lgkmcnt(10)
	v_mfma_f32_32x32x16_bf16 v[128:143], v[8:11], v[144:147], v[128:143]
	v_exp_f32_e32 v96, v82
	v_exp_f32_e32 v0, v97
	v_exp_f32_e32 v10, v81
	v_exp_f32_e32 v8, v100
	v_exp_f32_e32 v97, v84
	v_exp_f32_e32 v144, v99
	v_exp_f32_e32 v14, v83
	s_waitcnt lgkmcnt(9)
	v_mfma_f32_32x32x16_bf16 v[112:127], v[170:173], v[148:151], v[112:127]
	v_exp_f32_e32 v9, v102
	v_exp_f32_e32 v98, v86
	v_exp_f32_e32 v160, v101
	v_exp_f32_e32 v146, v85
	v_exp_f32_e32 v80, v104
	v_exp_f32_e32 v88, v88
	v_exp_f32_e32 v81, v106
	s_waitcnt lgkmcnt(8)
	v_mfma_f32_32x32x16_bf16 v[128:143], v[174:177], v[148:151], v[128:143]
	v_exp_f32_e32 v150, v103
	v_exp_f32_e32 v148, v87
	v_exp_f32_e32 v90, v90
	v_exp_f32_e32 v164, v105
	v_exp_f32_e32 v162, v89
	v_exp_f32_e32 v82, v108
	v_exp_f32_e32 v92, v92
	s_waitcnt lgkmcnt(7)
	v_mfma_f32_32x32x16_bf16 v[112:127], v[166:169], v[152:155], v[112:127]
	v_exp_f32_e32 v168, v107
	v_exp_f32_e32 v166, v91
	v_exp_f32_e32 v83, v110
	v_exp_f32_e32 v91, v94
	v_exp_f32_e32 v108, v109
	v_exp_f32_e32 v170, v93
	v_exp_f32_e32 v110, v111
	s_waitcnt lgkmcnt(6)
	v_mfma_f32_32x32x16_bf16 v[128:143], v[180:183], v[152:155], v[128:143]
	v_exp_f32_e32 v172, v95
	v_add_f32_e32 v11, v13, v6
	v_add_f32_e32 v15, v96, v7
	v_add_f32_e32 v147, v97, v8
	v_add_f32_e32 v149, v98, v9
	v_add_f32_e32 v163, v88, v80
	v_add_f32_e32 v167, v90, v81
	s_waitcnt lgkmcnt(5)
	v_mfma_f32_32x32x16_bf16 v[112:127], v[186:189], v[156:159], v[112:127]
	v_add_f32_e32 v171, v92, v82
	v_add_f32_e32 v173, v91, v83
	v_cvt_pk_bf16_f32 v6, v6, v0
	v_cvt_pk_bf16_f32 v7, v7, v144
	v_cvt_pk_bf16_f32 v8, v8, v160
	v_cvt_pk_bf16_f32 v9, v9, v150
	v_cvt_pk_bf16_f32 v80, v80, v164
	s_waitcnt lgkmcnt(4)
	v_mfma_f32_32x32x16_bf16 v[128:143], v[206:209], v[156:159], v[128:143]
	v_cvt_pk_bf16_f32 v81, v81, v168
	v_cvt_pk_bf16_f32 v82, v82, v108
	v_cvt_pk_bf16_f32 v83, v83, v110
	v_cvt_pk_bf16_f32 v84, v13, v10
	v_cvt_pk_bf16_f32 v85, v96, v14
	v_cvt_pk_bf16_f32 v86, v97, v146
	v_cvt_pk_bf16_f32 v87, v98, v148
	v_cvt_pk_bf16_f32 v88, v88, v162
	v_cvt_pk_bf16_f32 v89, v90, v166
	v_cvt_pk_bf16_f32 v90, v92, v170
	v_cvt_pk_bf16_f32 v91, v91, v172
	v_add_f32_e32 v10, v10, v0
	v_add_f32_e32 v11, v11, v1
	s_waitcnt lgkmcnt(3)
	v_mfma_f32_32x32x16_bf16 v[64:79], v[2:5], v[6:9], v[64:79]
	v_add_f32_e32 v145, v10, v11
	v_add_f32_e32 v2, v14, v144
	v_add_f32_e32 v3, v15, v145
	v_add_u32_e32 v13, s12, v203
	v_add_f32_e32 v161, v2, v3
	v_add_f32_e32 v2, v146, v160
	v_add_f32_e32 v3, v147, v161
	s_waitcnt lgkmcnt(2)
	v_mfma_f32_32x32x16_bf16 v[48:63], v[210:213], v[6:9], v[48:63]
	v_add_f32_e32 v151, v2, v3
	v_add_f32_e32 v2, v148, v150
	v_add_f32_e32 v3, v149, v151
	ds_read_b128 v[92:95], v13
	ds_read_b128 v[96:99], v13 offset:4096
	ds_read_b128 v[100:103], v13 offset:8192
	ds_read_b128 v[104:107], v13 offset:12288
	v_add_f32_e32 v165, v2, v3
	v_add_f32_e32 v2, v162, v164
	v_add_f32_e32 v3, v163, v165
	s_waitcnt lgkmcnt(5)
	v_mfma_f32_32x32x16_bf16 v[32:47], v[214:217], v[6:9], v[32:47]
	v_add_f32_e32 v169, v2, v3
	v_add_f32_e32 v2, v166, v168
	v_add_f32_e32 v3, v167, v169
	s_nop 0
	v_add_f32_e32 v109, v2, v3
	v_add_f32_e32 v2, v170, v108
	v_add_f32_e32 v3, v171, v109
	s_waitcnt lgkmcnt(4)
	v_mfma_f32_32x32x16_bf16 v[16:31], v[218:221], v[6:9], v[16:31]
	v_add_f32_e32 v111, v2, v3
	v_add_f32_e32 v2, v172, v110
	v_add_f32_e32 v3, v173, v111
	s_nop 0
	v_add_f32_e32 v0, v2, v3
	v_add_f32_e32 v184, v184, v0
	s_waitcnt lgkmcnt(3)
	v_mfma_f32_32x32x16_bf16 v[64:79], v[92:95], v[80:83], v[64:79]
	v_add_u32_e32 v0, s12, v202
	s_waitcnt lgkmcnt(2)
	v_mfma_f32_32x32x16_bf16 v[48:63], v[96:99], v[80:83], v[48:63]
	ds_read_b128 v[2:5], v0
	ds_read_b128 v[6:9], v0 offset:4096
	ds_read_b128 v[92:95], v0 offset:8192
	ds_read_b128 v[96:99], v0 offset:12288
	s_waitcnt lgkmcnt(5)
	v_mfma_f32_32x32x16_bf16 v[32:47], v[100:103], v[80:83], v[32:47]
	s_waitcnt lgkmcnt(4)
	v_mfma_f32_32x32x16_bf16 v[16:31], v[104:107], v[80:83], v[16:31]
	v_add_u32_e32 v0, s12, v179
	ds_read_b128 v[80:83], v0
	ds_read_b128 v[100:103], v0 offset:4096
	s_waitcnt lgkmcnt(5)
	v_mfma_f32_32x32x16_bf16 v[64:79], v[2:5], v[84:87], v[64:79]
	ds_read_b128 v[2:5], v0 offset:8192
	ds_read_b128 v[104:107], v0 offset:12288
	v_max_f32_e32 v0, v129, v129
	v_max_f32_e32 v10, v113, v113
	v_max_f32_e32 v0, v10, v0
	v_max3_f32 v10, v112, v128, v114
	v_max3_f32 v0, v0, v115, v131
	v_max3_f32 v10, v10, v130, v116
	v_max3_f32 v0, v0, v117, v133
	s_waitcnt lgkmcnt(6)
	v_mfma_f32_32x32x16_bf16 v[48:63], v[6:9], v[84:87], v[48:63]
	v_max3_f32 v6, v10, v132, v118
	v_max3_f32 v0, v0, v119, v135
	v_max3_f32 v6, v6, v134, v120
	v_max3_f32 v0, v0, v121, v137
	v_max3_f32 v6, v6, v136, v122
	v_max3_f32 v0, v0, v123, v139
	v_max3_f32 v6, v6, v138, v124
	s_waitcnt lgkmcnt(5)
	v_mfma_f32_32x32x16_bf16 v[32:47], v[92:95], v[84:87], v[32:47]
	v_max3_f32 v0, v0, v125, v141
	v_max3_f32 v6, v6, v140, v126
	v_max3_f32 v0, v0, v127, v143
	v_max3_f32 v0, v6, v142, v0
	v_mov_b32_e32 v6, v0
	s_nop 1
	v_permlane32_swap_b32_e32 v0, v6
	s_waitcnt lgkmcnt(4)
	v_mfma_f32_32x32x16_bf16 v[16:31], v[96:99], v[84:87], v[16:31]
	s_waitcnt lgkmcnt(3)
	v_mfma_f32_32x32x16_bf16 v[64:79], v[80:83], v[88:91], v[64:79]
	v_max_f32_e32 v0, v0, v0
	s_waitcnt lgkmcnt(2)
	v_mfma_f32_32x32x16_bf16 v[48:63], v[100:103], v[88:91], v[48:63]
	s_waitcnt lgkmcnt(1)
	v_mfma_f32_32x32x16_bf16 v[32:47], v[2:5], v[88:91], v[32:47]
	v_max_f32_e32 v2, v6, v6
	v_max_f32_e32 v0, v0, v2
	v_cmp_lt_f32_e32 vcc, s93, v0
	s_waitcnt lgkmcnt(0)
	v_mfma_f32_32x32x16_bf16 v[16:31], v[104:107], v[88:91], v[16:31]
	s_cbranch_vccz .LBB0_664
	v_max_f32_e32 v0, v0, v0
	v_max_f32_e32 v2, 0, v0
	v_exp_f32_e64 v0, -v2
	v_sub_f32_e32 v143, v143, v2
	v_sub_f32_e32 v142, v142, v2
	v_sub_f32_e32 v141, v141, v2
	v_sub_f32_e32 v140, v140, v2
	v_sub_f32_e32 v139, v139, v2
	v_sub_f32_e32 v138, v138, v2
	v_sub_f32_e32 v137, v137, v2
	v_sub_f32_e32 v136, v136, v2
	v_sub_f32_e32 v135, v135, v2
	v_sub_f32_e32 v134, v134, v2
	v_sub_f32_e32 v133, v133, v2
	v_sub_f32_e32 v132, v132, v2
	v_sub_f32_e32 v131, v131, v2
	v_sub_f32_e32 v130, v130, v2
	v_sub_f32_e32 v129, v129, v2
	v_sub_f32_e32 v128, v128, v2
	v_pk_mul_f32 v[78:79], v[78:79], v[0:1] op_sel_hi:[1,0]
	v_pk_mul_f32 v[76:77], v[76:77], v[0:1] op_sel_hi:[1,0]
	v_pk_mul_f32 v[74:75], v[74:75], v[0:1] op_sel_hi:[1,0]
	v_pk_mul_f32 v[72:73], v[72:73], v[0:1] op_sel_hi:[1,0]
	v_pk_mul_f32 v[70:71], v[70:71], v[0:1] op_sel_hi:[1,0]
	v_pk_mul_f32 v[68:69], v[68:69], v[0:1] op_sel_hi:[1,0]
	v_pk_mul_f32 v[66:67], v[66:67], v[0:1] op_sel_hi:[1,0]
	v_pk_mul_f32 v[64:65], v[64:65], v[0:1] op_sel_hi:[1,0]
	v_pk_mul_f32 v[62:63], v[62:63], v[0:1] op_sel_hi:[1,0]
	v_pk_mul_f32 v[60:61], v[60:61], v[0:1] op_sel_hi:[1,0]
	v_pk_mul_f32 v[58:59], v[58:59], v[0:1] op_sel_hi:[1,0]
	v_pk_mul_f32 v[56:57], v[56:57], v[0:1] op_sel_hi:[1,0]
	v_pk_mul_f32 v[54:55], v[54:55], v[0:1] op_sel_hi:[1,0]
	v_pk_mul_f32 v[52:53], v[52:53], v[0:1] op_sel_hi:[1,0]
	v_pk_mul_f32 v[50:51], v[50:51], v[0:1] op_sel_hi:[1,0]
	v_pk_mul_f32 v[48:49], v[48:49], v[0:1] op_sel_hi:[1,0]
	v_pk_mul_f32 v[46:47], v[0:1], v[46:47] op_sel_hi:[0,1]
	v_pk_mul_f32 v[44:45], v[0:1], v[44:45] op_sel_hi:[0,1]
	v_pk_mul_f32 v[42:43], v[0:1], v[42:43] op_sel_hi:[0,1]
	v_pk_mul_f32 v[40:41], v[0:1], v[40:41] op_sel_hi:[0,1]
	v_pk_mul_f32 v[38:39], v[0:1], v[38:39] op_sel_hi:[0,1]
	v_pk_mul_f32 v[36:37], v[0:1], v[36:37] op_sel_hi:[0,1]
	v_pk_mul_f32 v[34:35], v[0:1], v[34:35] op_sel_hi:[0,1]
	v_pk_mul_f32 v[32:33], v[0:1], v[32:33] op_sel_hi:[0,1]
	v_pk_mul_f32 v[30:31], v[0:1], v[30:31] op_sel_hi:[0,1]
	v_pk_mul_f32 v[28:29], v[0:1], v[28:29] op_sel_hi:[0,1]
	v_pk_mul_f32 v[26:27], v[0:1], v[26:27] op_sel_hi:[0,1]
	v_pk_mul_f32 v[24:25], v[0:1], v[24:25] op_sel_hi:[0,1]
	v_pk_mul_f32 v[22:23], v[0:1], v[22:23] op_sel_hi:[0,1]
	v_pk_mul_f32 v[20:21], v[0:1], v[20:21] op_sel_hi:[0,1]
	v_pk_mul_f32 v[18:19], v[0:1], v[18:19] op_sel_hi:[0,1]
	v_pk_mul_f32 v[16:17], v[0:1], v[16:17] op_sel_hi:[0,1]
	v_sub_f32_e32 v127, v127, v2
	v_sub_f32_e32 v126, v126, v2
	v_sub_f32_e32 v125, v125, v2
	v_sub_f32_e32 v124, v124, v2
	v_sub_f32_e32 v123, v123, v2
	v_sub_f32_e32 v122, v122, v2
	v_sub_f32_e32 v121, v121, v2
	v_sub_f32_e32 v120, v120, v2
	v_sub_f32_e32 v119, v119, v2
	v_sub_f32_e32 v118, v118, v2
	v_sub_f32_e32 v117, v117, v2
	v_sub_f32_e32 v116, v116, v2
	v_sub_f32_e32 v115, v115, v2
	v_sub_f32_e32 v114, v114, v2
	v_sub_f32_e32 v113, v113, v2
	v_sub_f32_e32 v112, v112, v2
	v_mul_f32_e32 v184, v184, v0
